# 128x256 K-loops: DMA for stage n+2 issued mid-stage (after 16 of the 32 MFMAs) instead of after the first five fragment reads
# baseline (speedup 1.0000x reference)
; #define BLOAD(A_, B_, kt) do { _Pragma("unroll") for (int i = 0; i < 4; ++i) { \
;     A_[i] = *(const u32x4*)((const char*)Ap + (aoff + (unsigned)(32 * i * lda + (kt) * 64) * 2u)); B_[i] = *(const u32x4*)((const char*)Wt + (woff + (unsigned)(32 * i * K + (kt) * 64) * 2u)); } } while (0)
; #define BLOAD(A_, B_, kt) do { _Pragma("unroll") for (int i = 0; i < 4; ++i) { \
;     A_[i] = *(const u32x4*)((const char*)Ap + (aoff + (unsigned)(32 * i * lda + (kt) * 64) * 2u)); B_[i] = *(const u32x4*)((const char*)Wt + (woff + (unsigned)(32 * i * K + (kt) * 64) * 2u)); } } while (0)
; #define BSTORE(A_, B_, buf) do { _Pragma("unroll") for (int i = 0; i < 4; ++i) { \
;     *(u32x4*)&As[(buf) * GBUF + (srow + 32 * i) * LDT + sc8] = A_[i]; \
;     *(u32x4*)&Bs[(buf) * GBUF + (srow + 32 * i) * LDT + sc8] = B_[i]; } } while (0)
; template <int NK>
; DI void gemm_run(PF& pf, const u16* __restrict__ Ap, int lda, const u16* __restrict__ Wt, f32x16 (&acc)[2][2], char* smem) {
;     ...
; #pragma unroll
;   for (int kt = 0; kt < nk; kt += 2) {
;     BCOMP(0);
;     BSTORE(pf.a1, pf.b1, 1);
;     if (kt + 3 < nk) BLOAD(pf.a1, pf.b1, kt + 3);
;     __syncthreads();
;     BCOMP(1);
;     if (kt + 2 < nk) { BSTORE(pf.a0, pf.b0, 0); if (kt + 4 < nk) BLOAD(pf.a0, pf.b0, kt + 4); }
;     __syncthreads();
;   }
.Lffn2_kloop:
	s_waitcnt vmcnt(6)
	s_barrier
	ds_read_b128 v[224:227], v126 offset:0
	ds_read_b128 v[240:243], v128 offset:0
	ds_read_b128 v[244:247], v128 offset:1024
	ds_read_b128 v[248:251], v128 offset:2048
	ds_read_b128 v[156:159], v128 offset:3072
	ds_read_b128 v[228:231], v126 offset:1024
	ds_read_b128 v[232:235], v126 offset:2048
	ds_read_b128 v[236:239], v126 offset:3072
	ds_read_b128 v[160:163], v128 offset:8192
	ds_read_b128 v[164:167], v128 offset:9216
	ds_read_b128 v[168:171], v128 offset:10240
	ds_read_b128 v[122:125], v128 offset:11264
	s_waitcnt lgkmcnt(10)
	v_mfma_f32_16x16x32_bf16 v[2:5], v[240:243], v[224:227], v[2:5]
	s_waitcnt lgkmcnt(9)
	v_mfma_f32_16x16x32_bf16 v[6:9], v[244:247], v[224:227], v[6:9]
	s_waitcnt lgkmcnt(8)
	v_mfma_f32_16x16x32_bf16 v[10:13], v[248:251], v[224:227], v[10:13]
	s_waitcnt lgkmcnt(7)
	v_mfma_f32_16x16x32_bf16 v[14:17], v[156:159], v[224:227], v[14:17]
	s_waitcnt lgkmcnt(6)
	v_mfma_f32_16x16x32_bf16 v[18:21], v[240:243], v[228:231], v[18:21]
	v_mfma_f32_16x16x32_bf16 v[22:25], v[244:247], v[228:231], v[22:25]
	v_mfma_f32_16x16x32_bf16 v[26:29], v[248:251], v[228:231], v[26:29]
	v_mfma_f32_16x16x32_bf16 v[30:33], v[156:159], v[228:231], v[30:33]
	s_waitcnt lgkmcnt(5)
	v_mfma_f32_16x16x32_bf16 v[34:37], v[240:243], v[232:235], v[34:37]
	v_mfma_f32_16x16x32_bf16 v[38:41], v[244:247], v[232:235], v[38:41]
	v_mfma_f32_16x16x32_bf16 v[42:45], v[248:251], v[232:235], v[42:45]
	v_mfma_f32_16x16x32_bf16 v[46:49], v[156:159], v[232:235], v[46:49]
	s_waitcnt lgkmcnt(4)
	v_mfma_f32_16x16x32_bf16 v[50:53], v[240:243], v[236:239], v[50:53]
	v_mfma_f32_16x16x32_bf16 v[54:57], v[244:247], v[236:239], v[54:57]
	v_mfma_f32_16x16x32_bf16 v[58:61], v[248:251], v[236:239], v[58:61]
	v_mfma_f32_16x16x32_bf16 v[62:65], v[156:159], v[236:239], v[62:65]
	s_add_u32 m0, s16, 0xc000
	s_add_u32 s42, s42, 0x100000
	s_addc_u32 s43, s43, 0
	global_load_lds_dwordx4 v137, s[42:43]
	global_load_lds_dwordx4 v150, s[42:43] offset:1024
	s_add_u32 m0, s0, 0xc000
	s_add_u32 s30, s30, 0x10000
	s_addc_u32 s31, s31, 0
	global_load_lds_dwordx4 v151, s[30:31]
	global_load_lds_dwordx4 v152, s[30:31] offset:1024
	global_load_lds_dwordx4 v153, s[30:31] offset:2048
	global_load_lds_dwordx4 v154, s[30:31] offset:3072
	s_waitcnt lgkmcnt(3)
	v_mfma_f32_16x16x32_bf16 v[74:77], v[160:163], v[224:227], v[74:77]
	s_waitcnt lgkmcnt(2)
	v_mfma_f32_16x16x32_bf16 v[78:81], v[164:167], v[224:227], v[78:81]
	s_waitcnt lgkmcnt(1)
	v_mfma_f32_16x16x32_bf16 v[82:85], v[168:171], v[224:227], v[82:85]
	s_waitcnt lgkmcnt(0)
	v_mfma_f32_16x16x32_bf16 v[86:89], v[122:125], v[224:227], v[86:89]
	v_mfma_f32_16x16x32_bf16 v[90:93], v[160:163], v[228:231], v[90:93]
	v_mfma_f32_16x16x32_bf16 v[94:97], v[164:167], v[228:231], v[94:97]
	v_mfma_f32_16x16x32_bf16 v[98:101], v[168:171], v[228:231], v[98:101]
	v_mfma_f32_16x16x32_bf16 v[102:105], v[122:125], v[228:231], v[102:105]
	v_mfma_f32_16x16x32_bf16 v[106:109], v[160:163], v[232:235], v[106:109]
	v_mfma_f32_16x16x32_bf16 v[110:113], v[164:167], v[232:235], v[110:113]
	v_mfma_f32_16x16x32_bf16 v[114:117], v[168:171], v[232:235], v[114:117]
	v_mfma_f32_16x16x32_bf16 v[118:121], v[122:125], v[232:235], v[118:121]
	v_mfma_f32_16x16x32_bf16 v[208:211], v[160:163], v[236:239], v[208:211]
	v_mfma_f32_16x16x32_bf16 v[212:215], v[164:167], v[236:239], v[212:215]
	v_mfma_f32_16x16x32_bf16 v[216:219], v[168:171], v[236:239], v[216:219]
	v_mfma_f32_16x16x32_bf16 v[220:223], v[122:125], v[236:239], v[220:223]
	s_waitcnt vmcnt(6)
	s_barrier
	ds_read_b128 v[224:227], v126 offset:24576
	ds_read_b128 v[240:243], v128 offset:24576
	ds_read_b128 v[244:247], v128 offset:25600
	ds_read_b128 v[248:251], v128 offset:26624
	ds_read_b128 v[156:159], v128 offset:27648
	ds_read_b128 v[228:231], v126 offset:25600
	ds_read_b128 v[232:235], v126 offset:26624
	ds_read_b128 v[236:239], v126 offset:27648
	ds_read_b128 v[160:163], v128 offset:32768
	ds_read_b128 v[164:167], v128 offset:33792
	ds_read_b128 v[168:171], v128 offset:34816
	ds_read_b128 v[122:125], v128 offset:35840
	s_waitcnt lgkmcnt(10)
	v_mfma_f32_16x16x32_bf16 v[2:5], v[240:243], v[224:227], v[2:5]
	s_waitcnt lgkmcnt(9)
	v_mfma_f32_16x16x32_bf16 v[6:9], v[244:247], v[224:227], v[6:9]
	s_waitcnt lgkmcnt(8)
	v_mfma_f32_16x16x32_bf16 v[10:13], v[248:251], v[224:227], v[10:13]
	s_waitcnt lgkmcnt(7)
	v_mfma_f32_16x16x32_bf16 v[14:17], v[156:159], v[224:227], v[14:17]
	s_waitcnt lgkmcnt(6)
	v_mfma_f32_16x16x32_bf16 v[18:21], v[240:243], v[228:231], v[18:21]
	v_mfma_f32_16x16x32_bf16 v[22:25], v[244:247], v[228:231], v[22:25]
	v_mfma_f32_16x16x32_bf16 v[26:29], v[248:251], v[228:231], v[26:29]
	v_mfma_f32_16x16x32_bf16 v[30:33], v[156:159], v[228:231], v[30:33]
	s_waitcnt lgkmcnt(5)
	v_mfma_f32_16x16x32_bf16 v[34:37], v[240:243], v[232:235], v[34:37]
	v_mfma_f32_16x16x32_bf16 v[38:41], v[244:247], v[232:235], v[38:41]
	v_mfma_f32_16x16x32_bf16 v[42:45], v[248:251], v[232:235], v[42:45]
	v_mfma_f32_16x16x32_bf16 v[46:49], v[156:159], v[232:235], v[46:49]
	s_waitcnt lgkmcnt(4)
	v_mfma_f32_16x16x32_bf16 v[50:53], v[240:243], v[236:239], v[50:53]
	v_mfma_f32_16x16x32_bf16 v[54:57], v[244:247], v[236:239], v[54:57]
	v_mfma_f32_16x16x32_bf16 v[58:61], v[248:251], v[236:239], v[58:61]
	v_mfma_f32_16x16x32_bf16 v[62:65], v[156:159], v[236:239], v[62:65]
	s_add_u32 m0, s16, 0x0
	s_add_u32 s42, s42, 0x100000
	s_addc_u32 s43, s43, 0
	global_load_lds_dwordx4 v137, s[42:43]
	global_load_lds_dwordx4 v150, s[42:43] offset:1024
	s_add_u32 m0, s0, 0x0
	s_add_u32 s30, s30, 0x10000
	s_addc_u32 s31, s31, 0
	global_load_lds_dwordx4 v151, s[30:31]
	global_load_lds_dwordx4 v152, s[30:31] offset:1024
	global_load_lds_dwordx4 v153, s[30:31] offset:2048
	global_load_lds_dwordx4 v154, s[30:31] offset:3072
	s_waitcnt lgkmcnt(3)
	v_mfma_f32_16x16x32_bf16 v[74:77], v[160:163], v[224:227], v[74:77]
	s_waitcnt lgkmcnt(2)
	v_mfma_f32_16x16x32_bf16 v[78:81], v[164:167], v[224:227], v[78:81]
	s_waitcnt lgkmcnt(1)
	v_mfma_f32_16x16x32_bf16 v[82:85], v[168:171], v[224:227], v[82:85]
	s_waitcnt lgkmcnt(0)
	v_mfma_f32_16x16x32_bf16 v[86:89], v[122:125], v[224:227], v[86:89]
	v_mfma_f32_16x16x32_bf16 v[90:93], v[160:163], v[228:231], v[90:93]
	v_mfma_f32_16x16x32_bf16 v[94:97], v[164:167], v[228:231], v[94:97]
	v_mfma_f32_16x16x32_bf16 v[98:101], v[168:171], v[228:231], v[98:101]
	v_mfma_f32_16x16x32_bf16 v[102:105], v[122:125], v[228:231], v[102:105]
	v_mfma_f32_16x16x32_bf16 v[106:109], v[160:163], v[232:235], v[106:109]
	v_mfma_f32_16x16x32_bf16 v[110:113], v[164:167], v[232:235], v[110:113]
	v_mfma_f32_16x16x32_bf16 v[114:117], v[168:171], v[232:235], v[114:117]
	v_mfma_f32_16x16x32_bf16 v[118:121], v[122:125], v[232:235], v[118:121]
	v_mfma_f32_16x16x32_bf16 v[208:211], v[160:163], v[236:239], v[208:211]
	v_mfma_f32_16x16x32_bf16 v[212:215], v[164:167], v[236:239], v[212:215]
	v_mfma_f32_16x16x32_bf16 v[216:219], v[168:171], v[236:239], v[216:219]
	v_mfma_f32_16x16x32_bf16 v[220:223], v[122:125], v[236:239], v[220:223]
	s_waitcnt vmcnt(6)
	s_barrier
; #define BLOAD(A_, B_, kt) do { _Pragma("unroll") for (int i = 0; i < 4; ++i) { \
;     A_[i] = *(const u32x4*)((const char*)Ap + (aoff + (unsigned)(32 * i * lda + (kt) * 64) * 2u)); B_[i] = *(const u32x4*)((const char*)Wt + (woff + (unsigned)(32 * i * K + (kt) * 64) * 2u)); } } while (0)
; #define BLOAD(A_, B_, kt) do { _Pragma("unroll") for (int i = 0; i < 4; ++i) { \
;     A_[i] = *(const u32x4*)((const char*)Ap + (aoff + (unsigned)(32 * i * lda + (kt) * 64) * 2u)); B_[i] = *(const u32x4*)((const char*)Wt + (woff + (unsigned)(32 * i * K + (kt) * 64) * 2u)); } } while (0)
; #define BSTORE(A_, B_, buf) do { _Pragma("unroll") for (int i = 0; i < 4; ++i) { \
;     *(u32x4*)&As[(buf) * GBUF + (srow + 32 * i) * LDT + sc8] = A_[i]; \
;     *(u32x4*)&Bs[(buf) * GBUF + (srow + 32 * i) * LDT + sc8] = B_[i]; } } while (0)
; template <int NK>
; DI void gemm_run(PF& pf, const u16* __restrict__ Ap, int lda, const u16* __restrict__ Wt, f32x16 (&acc)[2][2], char* smem) {
;     ...
; #pragma unroll
;   for (int kt = 0; kt < nk; kt += 2) {
;     BCOMP(0);
;     BSTORE(pf.a1, pf.b1, 1);
;     if (kt + 3 < nk) BLOAD(pf.a1, pf.b1, kt + 3);
;     __syncthreads();
;     BCOMP(1);
;     if (kt + 2 < nk) { BSTORE(pf.a0, pf.b0, 0); if (kt + 4 < nk) BLOAD(pf.a0, pf.b0, kt + 4); }
;     __syncthreads();
;   }
	ds_read_b128 v[224:227], v126 offset:49152
	ds_read_b128 v[240:243], v128 offset:49152
	ds_read_b128 v[244:247], v128 offset:50176
	ds_read_b128 v[248:251], v128 offset:51200
	ds_read_b128 v[156:159], v128 offset:52224
	ds_read_b128 v[228:231], v126 offset:50176
	ds_read_b128 v[232:235], v126 offset:51200
	ds_read_b128 v[236:239], v126 offset:52224
	ds_read_b128 v[160:163], v128 offset:57344
	ds_read_b128 v[164:167], v128 offset:58368
	ds_read_b128 v[168:171], v128 offset:59392
	ds_read_b128 v[122:125], v128 offset:60416
	s_waitcnt lgkmcnt(10)
	v_mfma_f32_16x16x32_bf16 v[2:5], v[240:243], v[224:227], v[2:5]
	s_waitcnt lgkmcnt(9)
	v_mfma_f32_16x16x32_bf16 v[6:9], v[244:247], v[224:227], v[6:9]
	s_waitcnt lgkmcnt(8)
	v_mfma_f32_16x16x32_bf16 v[10:13], v[248:251], v[224:227], v[10:13]
	s_waitcnt lgkmcnt(7)
	v_mfma_f32_16x16x32_bf16 v[14:17], v[156:159], v[224:227], v[14:17]
	s_waitcnt lgkmcnt(6)
	v_mfma_f32_16x16x32_bf16 v[18:21], v[240:243], v[228:231], v[18:21]
	v_mfma_f32_16x16x32_bf16 v[22:25], v[244:247], v[228:231], v[22:25]
	v_mfma_f32_16x16x32_bf16 v[26:29], v[248:251], v[228:231], v[26:29]
	v_mfma_f32_16x16x32_bf16 v[30:33], v[156:159], v[228:231], v[30:33]
	s_waitcnt lgkmcnt(5)
	v_mfma_f32_16x16x32_bf16 v[34:37], v[240:243], v[232:235], v[34:37]
	v_mfma_f32_16x16x32_bf16 v[38:41], v[244:247], v[232:235], v[38:41]
	v_mfma_f32_16x16x32_bf16 v[42:45], v[248:251], v[232:235], v[42:45]
	v_mfma_f32_16x16x32_bf16 v[46:49], v[156:159], v[232:235], v[46:49]
	s_waitcnt lgkmcnt(4)
	v_mfma_f32_16x16x32_bf16 v[50:53], v[240:243], v[236:239], v[50:53]
	v_mfma_f32_16x16x32_bf16 v[54:57], v[244:247], v[236:239], v[54:57]
	v_mfma_f32_16x16x32_bf16 v[58:61], v[248:251], v[236:239], v[58:61]
	v_mfma_f32_16x16x32_bf16 v[62:65], v[156:159], v[236:239], v[62:65]
	s_add_u32 m0, s16, 0x6000
	s_add_u32 s42, s42, 0x100000
	s_addc_u32 s43, s43, 0
	global_load_lds_dwordx4 v137, s[42:43]
	global_load_lds_dwordx4 v150, s[42:43] offset:1024
	s_add_u32 m0, s0, 0x6000
	s_add_u32 s30, s30, 0x10000
	s_addc_u32 s31, s31, 0
	global_load_lds_dwordx4 v151, s[30:31]
	global_load_lds_dwordx4 v152, s[30:31] offset:1024
	global_load_lds_dwordx4 v153, s[30:31] offset:2048
	global_load_lds_dwordx4 v154, s[30:31] offset:3072
	s_waitcnt lgkmcnt(3)
	v_mfma_f32_16x16x32_bf16 v[74:77], v[160:163], v[224:227], v[74:77]
	s_waitcnt lgkmcnt(2)
	v_mfma_f32_16x16x32_bf16 v[78:81], v[164:167], v[224:227], v[78:81]
	s_waitcnt lgkmcnt(1)
	v_mfma_f32_16x16x32_bf16 v[82:85], v[168:171], v[224:227], v[82:85]
	s_waitcnt lgkmcnt(0)
	v_mfma_f32_16x16x32_bf16 v[86:89], v[122:125], v[224:227], v[86:89]
	v_mfma_f32_16x16x32_bf16 v[90:93], v[160:163], v[228:231], v[90:93]
	v_mfma_f32_16x16x32_bf16 v[94:97], v[164:167], v[228:231], v[94:97]
	v_mfma_f32_16x16x32_bf16 v[98:101], v[168:171], v[228:231], v[98:101]
	v_mfma_f32_16x16x32_bf16 v[102:105], v[122:125], v[228:231], v[102:105]
	v_mfma_f32_16x16x32_bf16 v[106:109], v[160:163], v[232:235], v[106:109]
	v_mfma_f32_16x16x32_bf16 v[110:113], v[164:167], v[232:235], v[110:113]
	v_mfma_f32_16x16x32_bf16 v[114:117], v[168:171], v[232:235], v[114:117]
	v_mfma_f32_16x16x32_bf16 v[118:121], v[122:125], v[232:235], v[118:121]
	v_mfma_f32_16x16x32_bf16 v[208:211], v[160:163], v[236:239], v[208:211]
	v_mfma_f32_16x16x32_bf16 v[212:215], v[164:167], v[236:239], v[212:215]
	v_mfma_f32_16x16x32_bf16 v[216:219], v[168:171], v[236:239], v[216:219]
	v_mfma_f32_16x16x32_bf16 v[220:223], v[122:125], v[236:239], v[220:223]
	s_sub_u32 s46, s46, 1
	s_cmp_lg_u32 s46, 0
	s_cbranch_scc1 .Lffn2_kloop
	s_waitcnt vmcnt(6)
	s_barrier
; #define BLOAD(A_, B_, kt) do { _Pragma("unroll") for (int i = 0; i < 4; ++i) { \
;     A_[i] = *(const u32x4*)((const char*)Ap + (aoff + (unsigned)(32 * i * lda + (kt) * 64) * 2u)); B_[i] = *(const u32x4*)((const char*)Wt + (woff + (unsigned)(32 * i * K + (kt) * 64) * 2u)); } } while (0)
; #define BLOAD(A_, B_, kt) do { _Pragma("unroll") for (int i = 0; i < 4; ++i) { \
;     A_[i] = *(const u32x4*)((const char*)Ap + (aoff + (unsigned)(32 * i * lda + (kt) * 64) * 2u)); B_[i] = *(const u32x4*)((const char*)Wt + (woff + (unsigned)(32 * i * K + (kt) * 64) * 2u)); } } while (0)
; #define BSTORE(A_, B_, buf) do { _Pragma("unroll") for (int i = 0; i < 4; ++i) { \
;     *(u32x4*)&As[(buf) * GBUF + (srow + 32 * i) * LDT + sc8] = A_[i]; \
;     *(u32x4*)&Bs[(buf) * GBUF + (srow + 32 * i) * LDT + sc8] = B_[i]; } } while (0)
; template <int NK>
; DI void gemm_run(PF& pf, const u16* __restrict__ Ap, int lda, const u16* __restrict__ Wt, f32x16 (&acc)[2][2], char* smem) {
;     ...
; #pragma unroll
;   for (int kt = 0; kt < nk; kt += 2) {
;     BCOMP(0);
;     BSTORE(pf.a1, pf.b1, 1);
;     if (kt + 3 < nk) BLOAD(pf.a1, pf.b1, kt + 3);
;     __syncthreads();
;     BCOMP(1);
;     if (kt + 2 < nk) { BSTORE(pf.a0, pf.b0, 0); if (kt + 4 < nk) BLOAD(pf.a0, pf.b0, kt + 4); }
;     __syncthreads();
;   }
	ds_read_b128 v[224:227], v126 offset:0
	ds_read_b128 v[240:243], v128 offset:0
	ds_read_b128 v[244:247], v128 offset:1024
	ds_read_b128 v[248:251], v128 offset:2048
	ds_read_b128 v[156:159], v128 offset:3072
	ds_read_b128 v[228:231], v126 offset:1024
	ds_read_b128 v[232:235], v126 offset:2048
	ds_read_b128 v[236:239], v126 offset:3072
	ds_read_b128 v[160:163], v128 offset:8192
	ds_read_b128 v[164:167], v128 offset:9216
	ds_read_b128 v[168:171], v128 offset:10240
	ds_read_b128 v[122:125], v128 offset:11264
	s_waitcnt lgkmcnt(10)
	v_mfma_f32_16x16x32_bf16 v[2:5], v[240:243], v[224:227], v[2:5]
	s_waitcnt lgkmcnt(9)
	v_mfma_f32_16x16x32_bf16 v[6:9], v[244:247], v[224:227], v[6:9]
	s_waitcnt lgkmcnt(8)
	v_mfma_f32_16x16x32_bf16 v[10:13], v[248:251], v[224:227], v[10:13]
	s_waitcnt lgkmcnt(7)
	v_mfma_f32_16x16x32_bf16 v[14:17], v[156:159], v[224:227], v[14:17]
	s_waitcnt lgkmcnt(6)
	v_mfma_f32_16x16x32_bf16 v[18:21], v[240:243], v[228:231], v[18:21]
	v_mfma_f32_16x16x32_bf16 v[22:25], v[244:247], v[228:231], v[22:25]
	v_mfma_f32_16x16x32_bf16 v[26:29], v[248:251], v[228:231], v[26:29]
	v_mfma_f32_16x16x32_bf16 v[30:33], v[156:159], v[228:231], v[30:33]
	s_waitcnt lgkmcnt(5)
	v_mfma_f32_16x16x32_bf16 v[34:37], v[240:243], v[232:235], v[34:37]
	v_mfma_f32_16x16x32_bf16 v[38:41], v[244:247], v[232:235], v[38:41]
	v_mfma_f32_16x16x32_bf16 v[42:45], v[248:251], v[232:235], v[42:45]
	v_mfma_f32_16x16x32_bf16 v[46:49], v[156:159], v[232:235], v[46:49]
	s_waitcnt lgkmcnt(4)
	v_mfma_f32_16x16x32_bf16 v[50:53], v[240:243], v[236:239], v[50:53]
	v_mfma_f32_16x16x32_bf16 v[54:57], v[244:247], v[236:239], v[54:57]
	v_mfma_f32_16x16x32_bf16 v[58:61], v[248:251], v[236:239], v[58:61]
	v_mfma_f32_16x16x32_bf16 v[62:65], v[156:159], v[236:239], v[62:65]
	s_waitcnt lgkmcnt(3)
	v_mfma_f32_16x16x32_bf16 v[74:77], v[160:163], v[224:227], v[74:77]
	s_waitcnt lgkmcnt(2)
	v_mfma_f32_16x16x32_bf16 v[78:81], v[164:167], v[224:227], v[78:81]
	s_waitcnt lgkmcnt(1)
	v_mfma_f32_16x16x32_bf16 v[82:85], v[168:171], v[224:227], v[82:85]
	s_waitcnt lgkmcnt(0)
	v_mfma_f32_16x16x32_bf16 v[86:89], v[122:125], v[224:227], v[86:89]
	v_mfma_f32_16x16x32_bf16 v[90:93], v[160:163], v[228:231], v[90:93]
	v_mfma_f32_16x16x32_bf16 v[94:97], v[164:167], v[228:231], v[94:97]
	v_mfma_f32_16x16x32_bf16 v[98:101], v[168:171], v[228:231], v[98:101]
	v_mfma_f32_16x16x32_bf16 v[102:105], v[122:125], v[228:231], v[102:105]
	v_mfma_f32_16x16x32_bf16 v[106:109], v[160:163], v[232:235], v[106:109]
	v_mfma_f32_16x16x32_bf16 v[110:113], v[164:167], v[232:235], v[110:113]
	v_mfma_f32_16x16x32_bf16 v[114:117], v[168:171], v[232:235], v[114:117]
	v_mfma_f32_16x16x32_bf16 v[118:121], v[122:125], v[232:235], v[118:121]
	v_mfma_f32_16x16x32_bf16 v[208:211], v[160:163], v[236:239], v[208:211]
	v_mfma_f32_16x16x32_bf16 v[212:215], v[164:167], v[236:239], v[212:215]
	v_mfma_f32_16x16x32_bf16 v[216:219], v[168:171], v[236:239], v[216:219]
	v_mfma_f32_16x16x32_bf16 v[220:223], v[122:125], v[236:239], v[220:223]
	s_waitcnt vmcnt(0)
	s_barrier
	ds_read_b128 v[224:227], v126 offset:24576
	ds_read_b128 v[240:243], v128 offset:24576
	ds_read_b128 v[244:247], v128 offset:25600
	ds_read_b128 v[248:251], v128 offset:26624
	ds_read_b128 v[156:159], v128 offset:27648
	ds_read_b128 v[228:231], v126 offset:25600
	ds_read_b128 v[232:235], v126 offset:26624
	ds_read_b128 v[236:239], v126 offset:27648
	ds_read_b128 v[160:163], v128 offset:32768
	ds_read_b128 v[164:167], v128 offset:33792
	ds_read_b128 v[168:171], v128 offset:34816
	ds_read_b128 v[122:125], v128 offset:35840
	s_waitcnt lgkmcnt(10)
	v_mfma_f32_16x16x32_bf16 v[2:5], v[240:243], v[224:227], v[2:5]
	s_waitcnt lgkmcnt(9)
	v_mfma_f32_16x16x32_bf16 v[6:9], v[244:247], v[224:227], v[6:9]
	s_waitcnt lgkmcnt(8)
	v_mfma_f32_16x16x32_bf16 v[10:13], v[248:251], v[224:227], v[10:13]
	s_waitcnt lgkmcnt(7)
	v_mfma_f32_16x16x32_bf16 v[14:17], v[156:159], v[224:227], v[14:17]
	s_waitcnt lgkmcnt(6)
	v_mfma_f32_16x16x32_bf16 v[18:21], v[240:243], v[228:231], v[18:21]
	v_mfma_f32_16x16x32_bf16 v[22:25], v[244:247], v[228:231], v[22:25]
	v_mfma_f32_16x16x32_bf16 v[26:29], v[248:251], v[228:231], v[26:29]
	v_mfma_f32_16x16x32_bf16 v[30:33], v[156:159], v[228:231], v[30:33]
	s_waitcnt lgkmcnt(5)
	v_mfma_f32_16x16x32_bf16 v[34:37], v[240:243], v[232:235], v[34:37]
	v_mfma_f32_16x16x32_bf16 v[38:41], v[244:247], v[232:235], v[38:41]
	v_mfma_f32_16x16x32_bf16 v[42:45], v[248:251], v[232:235], v[42:45]
	v_mfma_f32_16x16x32_bf16 v[46:49], v[156:159], v[232:235], v[46:49]
	s_waitcnt lgkmcnt(4)
	v_mfma_f32_16x16x32_bf16 v[50:53], v[240:243], v[236:239], v[50:53]
	v_mfma_f32_16x16x32_bf16 v[54:57], v[244:247], v[236:239], v[54:57]
	v_mfma_f32_16x16x32_bf16 v[58:61], v[248:251], v[236:239], v[58:61]
	v_mfma_f32_16x16x32_bf16 v[62:65], v[156:159], v[236:239], v[62:65]
	s_waitcnt lgkmcnt(3)
	v_mfma_f32_16x16x32_bf16 v[74:77], v[160:163], v[224:227], v[74:77]
	s_waitcnt lgkmcnt(2)
	v_mfma_f32_16x16x32_bf16 v[78:81], v[164:167], v[224:227], v[78:81]
	s_waitcnt lgkmcnt(1)
	v_mfma_f32_16x16x32_bf16 v[82:85], v[168:171], v[224:227], v[82:85]
	s_waitcnt lgkmcnt(0)
	v_mfma_f32_16x16x32_bf16 v[86:89], v[122:125], v[224:227], v[86:89]
	v_mfma_f32_16x16x32_bf16 v[90:93], v[160:163], v[228:231], v[90:93]
	v_mfma_f32_16x16x32_bf16 v[94:97], v[164:167], v[228:231], v[94:97]
	v_mfma_f32_16x16x32_bf16 v[98:101], v[168:171], v[228:231], v[98:101]
	v_mfma_f32_16x16x32_bf16 v[102:105], v[122:125], v[228:231], v[102:105]
	v_mfma_f32_16x16x32_bf16 v[106:109], v[160:163], v[232:235], v[106:109]
	v_mfma_f32_16x16x32_bf16 v[110:113], v[164:167], v[232:235], v[110:113]
	v_mfma_f32_16x16x32_bf16 v[114:117], v[168:171], v[232:235], v[114:117]
	v_mfma_f32_16x16x32_bf16 v[118:121], v[122:125], v[232:235], v[118:121]
	v_mfma_f32_16x16x32_bf16 v[208:211], v[160:163], v[236:239], v[208:211]
	v_mfma_f32_16x16x32_bf16 v[212:215], v[164:167], v[236:239], v[212:215]
	v_mfma_f32_16x16x32_bf16 v[216:219], v[168:171], v[236:239], v[216:219]
	v_mfma_f32_16x16x32_bf16 v[220:223], v[122:125], v[236:239], v[220:223]
	s_barrier
	s_mov_b32 s16, 0

; #define BLOAD(A_, B_, kt) do { _Pragma("unroll") for (int i = 0; i < 4; ++i) { \
;     A_[i] = *(const u32x4*)((const char*)Ap + (aoff + (unsigned)(32 * i * lda + (kt) * 64) * 2u)); B_[i] = *(const u32x4*)((const char*)Wt + (woff + (unsigned)(32 * i * K + (kt) * 64) * 2u)); } } while (0)
; #define BLOAD(A_, B_, kt) do { _Pragma("unroll") for (int i = 0; i < 4; ++i) { \
;     A_[i] = *(const u32x4*)((const char*)Ap + (aoff + (unsigned)(32 * i * lda + (kt) * 64) * 2u)); B_[i] = *(const u32x4*)((const char*)Wt + (woff + (unsigned)(32 * i * K + (kt) * 64) * 2u)); } } while (0)
; #define BSTORE(A_, B_, buf) do { _Pragma("unroll") for (int i = 0; i < 4; ++i) { \
;     *(u32x4*)&As[(buf) * GBUF + (srow + 32 * i) * LDT + sc8] = A_[i]; \
;     *(u32x4*)&Bs[(buf) * GBUF + (srow + 32 * i) * LDT + sc8] = B_[i]; } } while (0)
; template <int NK>
; DI void gemm_run(PF& pf, const u16* __restrict__ Ap, int lda, const u16* __restrict__ Wt, f32x16 (&acc)[2][2], char* smem) {
;     ...
; #pragma unroll
;   for (int kt = 0; kt < nk; kt += 2) {
;     BCOMP(0);
;     BSTORE(pf.a1, pf.b1, 1);
;     if (kt + 3 < nk) BLOAD(pf.a1, pf.b1, kt + 3);
;     __syncthreads();
;     BCOMP(1);
;     if (kt + 2 < nk) { BSTORE(pf.a0, pf.b0, 0); if (kt + 4 < nk) BLOAD(pf.a0, pf.b0, kt + 4); }
;     __syncthreads();
;   }
.Lffn1_kloop:
	s_waitcnt vmcnt(6)
	s_barrier
	ds_read_b128 v[208:211], v138 offset:0
	ds_read_b128 v[224:227], v140 offset:0
	ds_read_b128 v[228:231], v140 offset:1024
	ds_read_b128 v[232:235], v140 offset:2048
	ds_read_b128 v[236:239], v140 offset:3072
	ds_read_b128 v[212:215], v138 offset:1024
	ds_read_b128 v[216:219], v138 offset:2048
	ds_read_b128 v[220:223], v138 offset:3072
	ds_read_b128 v[240:243], v140 offset:8192
	ds_read_b128 v[244:247], v140 offset:9216
	ds_read_b128 v[248:251], v140 offset:10240
	ds_read_b128 v[156:159], v140 offset:11264
	s_waitcnt lgkmcnt(10)
	v_mfma_f32_16x16x32_bf16 v[2:5], v[224:227], v[208:211], v[2:5]
	s_waitcnt lgkmcnt(9)
	v_mfma_f32_16x16x32_bf16 v[6:9], v[228:231], v[208:211], v[6:9]
	s_waitcnt lgkmcnt(8)
	v_mfma_f32_16x16x32_bf16 v[10:13], v[232:235], v[208:211], v[10:13]
	s_waitcnt lgkmcnt(7)
	v_mfma_f32_16x16x32_bf16 v[14:17], v[236:239], v[208:211], v[14:17]
	s_waitcnt lgkmcnt(6)
	v_mfma_f32_16x16x32_bf16 v[18:21], v[224:227], v[212:215], v[18:21]
	v_mfma_f32_16x16x32_bf16 v[22:25], v[228:231], v[212:215], v[22:25]
	v_mfma_f32_16x16x32_bf16 v[26:29], v[232:235], v[212:215], v[26:29]
	v_mfma_f32_16x16x32_bf16 v[30:33], v[236:239], v[212:215], v[30:33]
	s_waitcnt lgkmcnt(5)
	v_mfma_f32_16x16x32_bf16 v[34:37], v[224:227], v[216:219], v[34:37]
	v_mfma_f32_16x16x32_bf16 v[38:41], v[228:231], v[216:219], v[38:41]
	v_mfma_f32_16x16x32_bf16 v[42:45], v[232:235], v[216:219], v[42:45]
	v_mfma_f32_16x16x32_bf16 v[46:49], v[236:239], v[216:219], v[46:49]
	s_waitcnt lgkmcnt(4)
	v_mfma_f32_16x16x32_bf16 v[50:53], v[224:227], v[220:223], v[50:53]
	v_mfma_f32_16x16x32_bf16 v[54:57], v[228:231], v[220:223], v[54:57]
	v_mfma_f32_16x16x32_bf16 v[58:61], v[232:235], v[220:223], v[58:61]
	v_mfma_f32_16x16x32_bf16 v[62:65], v[236:239], v[220:223], v[62:65]
	s_add_u32 m0, s42, 0xc000
	s_add_u32 s28, s28, 0x100000
	s_addc_u32 s29, s29, 0
	global_load_lds_dwordx4 v142, s[28:29]
	global_load_lds_dwordx4 v143, s[28:29] offset:1024
	s_add_u32 m0, s43, 0xc000
	s_add_u32 s30, s30, 0x40000
	s_addc_u32 s31, s31, 0
	global_load_lds_dwordx4 v144, s[30:31]
	global_load_lds_dwordx4 v145, s[30:31] offset:1024
	global_load_lds_dwordx4 v146, s[30:31] offset:2048
	global_load_lds_dwordx4 v147, s[30:31] offset:3072
	s_waitcnt lgkmcnt(3)
	v_mfma_f32_16x16x32_bf16 v[74:77], v[240:243], v[208:211], v[74:77]
	s_waitcnt lgkmcnt(2)
	v_mfma_f32_16x16x32_bf16 v[78:81], v[244:247], v[208:211], v[78:81]
	s_waitcnt lgkmcnt(1)
	v_mfma_f32_16x16x32_bf16 v[82:85], v[248:251], v[208:211], v[82:85]
	s_waitcnt lgkmcnt(0)
	v_mfma_f32_16x16x32_bf16 v[86:89], v[156:159], v[208:211], v[86:89]
	v_mfma_f32_16x16x32_bf16 v[90:93], v[240:243], v[212:215], v[90:93]
	v_mfma_f32_16x16x32_bf16 v[94:97], v[244:247], v[212:215], v[94:97]
	v_mfma_f32_16x16x32_bf16 v[98:101], v[248:251], v[212:215], v[98:101]
	v_mfma_f32_16x16x32_bf16 v[102:105], v[156:159], v[212:215], v[102:105]
	v_mfma_f32_16x16x32_bf16 v[106:109], v[240:243], v[216:219], v[106:109]
	v_mfma_f32_16x16x32_bf16 v[110:113], v[244:247], v[216:219], v[110:113]
	v_mfma_f32_16x16x32_bf16 v[114:117], v[248:251], v[216:219], v[114:117]
	v_mfma_f32_16x16x32_bf16 v[118:121], v[156:159], v[216:219], v[118:121]
	v_mfma_f32_16x16x32_bf16 v[122:125], v[240:243], v[220:223], v[122:125]
	v_mfma_f32_16x16x32_bf16 v[126:129], v[244:247], v[220:223], v[126:129]
	v_mfma_f32_16x16x32_bf16 v[130:133], v[248:251], v[220:223], v[130:133]
	v_mfma_f32_16x16x32_bf16 v[134:137], v[156:159], v[220:223], v[134:137]
	s_waitcnt vmcnt(6)
	s_barrier
	ds_read_b128 v[208:211], v138 offset:24576
	ds_read_b128 v[224:227], v140 offset:24576
	ds_read_b128 v[228:231], v140 offset:25600
	ds_read_b128 v[232:235], v140 offset:26624
	ds_read_b128 v[236:239], v140 offset:27648
	ds_read_b128 v[212:215], v138 offset:25600
	ds_read_b128 v[216:219], v138 offset:26624
	ds_read_b128 v[220:223], v138 offset:27648
	ds_read_b128 v[240:243], v140 offset:32768
	ds_read_b128 v[244:247], v140 offset:33792
	ds_read_b128 v[248:251], v140 offset:34816
	ds_read_b128 v[156:159], v140 offset:35840
	s_waitcnt lgkmcnt(10)
	v_mfma_f32_16x16x32_bf16 v[2:5], v[224:227], v[208:211], v[2:5]
	s_waitcnt lgkmcnt(9)
	v_mfma_f32_16x16x32_bf16 v[6:9], v[228:231], v[208:211], v[6:9]
	s_waitcnt lgkmcnt(8)
	v_mfma_f32_16x16x32_bf16 v[10:13], v[232:235], v[208:211], v[10:13]
	s_waitcnt lgkmcnt(7)
	v_mfma_f32_16x16x32_bf16 v[14:17], v[236:239], v[208:211], v[14:17]
	s_waitcnt lgkmcnt(6)
	v_mfma_f32_16x16x32_bf16 v[18:21], v[224:227], v[212:215], v[18:21]
	v_mfma_f32_16x16x32_bf16 v[22:25], v[228:231], v[212:215], v[22:25]
	v_mfma_f32_16x16x32_bf16 v[26:29], v[232:235], v[212:215], v[26:29]
	v_mfma_f32_16x16x32_bf16 v[30:33], v[236:239], v[212:215], v[30:33]
	s_waitcnt lgkmcnt(5)
	v_mfma_f32_16x16x32_bf16 v[34:37], v[224:227], v[216:219], v[34:37]
	v_mfma_f32_16x16x32_bf16 v[38:41], v[228:231], v[216:219], v[38:41]
	v_mfma_f32_16x16x32_bf16 v[42:45], v[232:235], v[216:219], v[42:45]
	v_mfma_f32_16x16x32_bf16 v[46:49], v[236:239], v[216:219], v[46:49]
	s_waitcnt lgkmcnt(4)
	v_mfma_f32_16x16x32_bf16 v[50:53], v[224:227], v[220:223], v[50:53]
	v_mfma_f32_16x16x32_bf16 v[54:57], v[228:231], v[220:223], v[54:57]
	v_mfma_f32_16x16x32_bf16 v[58:61], v[232:235], v[220:223], v[58:61]
	v_mfma_f32_16x16x32_bf16 v[62:65], v[236:239], v[220:223], v[62:65]
	s_add_u32 m0, s42, 0x0
	s_add_u32 s28, s28, 0x100000
	s_addc_u32 s29, s29, 0
	global_load_lds_dwordx4 v142, s[28:29]
	global_load_lds_dwordx4 v143, s[28:29] offset:1024
	s_add_u32 m0, s43, 0x0
	s_add_u32 s30, s30, 0x40000
	s_addc_u32 s31, s31, 0
	global_load_lds_dwordx4 v144, s[30:31]
	global_load_lds_dwordx4 v145, s[30:31] offset:1024
	global_load_lds_dwordx4 v146, s[30:31] offset:2048
	global_load_lds_dwordx4 v147, s[30:31] offset:3072
	s_waitcnt lgkmcnt(3)
	v_mfma_f32_16x16x32_bf16 v[74:77], v[240:243], v[208:211], v[74:77]
	s_waitcnt lgkmcnt(2)
	v_mfma_f32_16x16x32_bf16 v[78:81], v[244:247], v[208:211], v[78:81]
	s_waitcnt lgkmcnt(1)
	v_mfma_f32_16x16x32_bf16 v[82:85], v[248:251], v[208:211], v[82:85]
	s_waitcnt lgkmcnt(0)
	v_mfma_f32_16x16x32_bf16 v[86:89], v[156:159], v[208:211], v[86:89]
	v_mfma_f32_16x16x32_bf16 v[90:93], v[240:243], v[212:215], v[90:93]
	v_mfma_f32_16x16x32_bf16 v[94:97], v[244:247], v[212:215], v[94:97]
	v_mfma_f32_16x16x32_bf16 v[98:101], v[248:251], v[212:215], v[98:101]
	v_mfma_f32_16x16x32_bf16 v[102:105], v[156:159], v[212:215], v[102:105]
	v_mfma_f32_16x16x32_bf16 v[106:109], v[240:243], v[216:219], v[106:109]
	v_mfma_f32_16x16x32_bf16 v[110:113], v[244:247], v[216:219], v[110:113]
	v_mfma_f32_16x16x32_bf16 v[114:117], v[248:251], v[216:219], v[114:117]
	v_mfma_f32_16x16x32_bf16 v[118:121], v[156:159], v[216:219], v[118:121]
	v_mfma_f32_16x16x32_bf16 v[122:125], v[240:243], v[220:223], v[122:125]
	v_mfma_f32_16x16x32_bf16 v[126:129], v[244:247], v[220:223], v[126:129]
	v_mfma_f32_16x16x32_bf16 v[130:133], v[248:251], v[220:223], v[130:133]
	v_mfma_f32_16x16x32_bf16 v[134:137], v[156:159], v[220:223], v[134:137]
	s_waitcnt vmcnt(6)
	s_barrier
; #define BLOAD(A_, B_, kt) do { _Pragma("unroll") for (int i = 0; i < 4; ++i) { \
;     A_[i] = *(const u32x4*)((const char*)Ap + (aoff + (unsigned)(32 * i * lda + (kt) * 64) * 2u)); B_[i] = *(const u32x4*)((const char*)Wt + (woff + (unsigned)(32 * i * K + (kt) * 64) * 2u)); } } while (0)
; #define BLOAD(A_, B_, kt) do { _Pragma("unroll") for (int i = 0; i < 4; ++i) { \
;     A_[i] = *(const u32x4*)((const char*)Ap + (aoff + (unsigned)(32 * i * lda + (kt) * 64) * 2u)); B_[i] = *(const u32x4*)((const char*)Wt + (woff + (unsigned)(32 * i * K + (kt) * 64) * 2u)); } } while (0)
; #define BSTORE(A_, B_, buf) do { _Pragma("unroll") for (int i = 0; i < 4; ++i) { \
;     *(u32x4*)&As[(buf) * GBUF + (srow + 32 * i) * LDT + sc8] = A_[i]; \
;     *(u32x4*)&Bs[(buf) * GBUF + (srow + 32 * i) * LDT + sc8] = B_[i]; } } while (0)
; template <int NK>
; DI void gemm_run(PF& pf, const u16* __restrict__ Ap, int lda, const u16* __restrict__ Wt, f32x16 (&acc)[2][2], char* smem) {
;     ...
; #pragma unroll
;   for (int kt = 0; kt < nk; kt += 2) {
;     BCOMP(0);
;     BSTORE(pf.a1, pf.b1, 1);
;     if (kt + 3 < nk) BLOAD(pf.a1, pf.b1, kt + 3);
;     __syncthreads();
;     BCOMP(1);
;     if (kt + 2 < nk) { BSTORE(pf.a0, pf.b0, 0); if (kt + 4 < nk) BLOAD(pf.a0, pf.b0, kt + 4); }
;     __syncthreads();
;   }
	ds_read_b128 v[208:211], v138 offset:49152
	ds_read_b128 v[224:227], v140 offset:49152
	ds_read_b128 v[228:231], v140 offset:50176
	ds_read_b128 v[232:235], v140 offset:51200
	ds_read_b128 v[236:239], v140 offset:52224
	ds_read_b128 v[212:215], v138 offset:50176
	ds_read_b128 v[216:219], v138 offset:51200
	ds_read_b128 v[220:223], v138 offset:52224
	ds_read_b128 v[240:243], v140 offset:57344
	ds_read_b128 v[244:247], v140 offset:58368
	ds_read_b128 v[248:251], v140 offset:59392
	ds_read_b128 v[156:159], v140 offset:60416
	s_waitcnt lgkmcnt(10)
	v_mfma_f32_16x16x32_bf16 v[2:5], v[224:227], v[208:211], v[2:5]
	s_waitcnt lgkmcnt(9)
	v_mfma_f32_16x16x32_bf16 v[6:9], v[228:231], v[208:211], v[6:9]
	s_waitcnt lgkmcnt(8)
	v_mfma_f32_16x16x32_bf16 v[10:13], v[232:235], v[208:211], v[10:13]
	s_waitcnt lgkmcnt(7)
	v_mfma_f32_16x16x32_bf16 v[14:17], v[236:239], v[208:211], v[14:17]
	s_waitcnt lgkmcnt(6)
	v_mfma_f32_16x16x32_bf16 v[18:21], v[224:227], v[212:215], v[18:21]
	v_mfma_f32_16x16x32_bf16 v[22:25], v[228:231], v[212:215], v[22:25]
	v_mfma_f32_16x16x32_bf16 v[26:29], v[232:235], v[212:215], v[26:29]
	v_mfma_f32_16x16x32_bf16 v[30:33], v[236:239], v[212:215], v[30:33]
	s_waitcnt lgkmcnt(5)
	v_mfma_f32_16x16x32_bf16 v[34:37], v[224:227], v[216:219], v[34:37]
	v_mfma_f32_16x16x32_bf16 v[38:41], v[228:231], v[216:219], v[38:41]
	v_mfma_f32_16x16x32_bf16 v[42:45], v[232:235], v[216:219], v[42:45]
	v_mfma_f32_16x16x32_bf16 v[46:49], v[236:239], v[216:219], v[46:49]
	s_waitcnt lgkmcnt(4)
	v_mfma_f32_16x16x32_bf16 v[50:53], v[224:227], v[220:223], v[50:53]
	v_mfma_f32_16x16x32_bf16 v[54:57], v[228:231], v[220:223], v[54:57]
	v_mfma_f32_16x16x32_bf16 v[58:61], v[232:235], v[220:223], v[58:61]
	v_mfma_f32_16x16x32_bf16 v[62:65], v[236:239], v[220:223], v[62:65]
	s_add_u32 m0, s42, 0x6000
	s_add_u32 s28, s28, 0x100000
	s_addc_u32 s29, s29, 0
	global_load_lds_dwordx4 v142, s[28:29]
	global_load_lds_dwordx4 v143, s[28:29] offset:1024
	s_add_u32 m0, s43, 0x6000
	s_add_u32 s30, s30, 0x40000
	s_addc_u32 s31, s31, 0
	global_load_lds_dwordx4 v144, s[30:31]
	global_load_lds_dwordx4 v145, s[30:31] offset:1024
	global_load_lds_dwordx4 v146, s[30:31] offset:2048
	global_load_lds_dwordx4 v147, s[30:31] offset:3072
	s_waitcnt lgkmcnt(3)
	v_mfma_f32_16x16x32_bf16 v[74:77], v[240:243], v[208:211], v[74:77]
	s_waitcnt lgkmcnt(2)
	v_mfma_f32_16x16x32_bf16 v[78:81], v[244:247], v[208:211], v[78:81]
	s_waitcnt lgkmcnt(1)
	v_mfma_f32_16x16x32_bf16 v[82:85], v[248:251], v[208:211], v[82:85]
	s_waitcnt lgkmcnt(0)
	v_mfma_f32_16x16x32_bf16 v[86:89], v[156:159], v[208:211], v[86:89]
	v_mfma_f32_16x16x32_bf16 v[90:93], v[240:243], v[212:215], v[90:93]
	v_mfma_f32_16x16x32_bf16 v[94:97], v[244:247], v[212:215], v[94:97]
	v_mfma_f32_16x16x32_bf16 v[98:101], v[248:251], v[212:215], v[98:101]
	v_mfma_f32_16x16x32_bf16 v[102:105], v[156:159], v[212:215], v[102:105]
	v_mfma_f32_16x16x32_bf16 v[106:109], v[240:243], v[216:219], v[106:109]
	v_mfma_f32_16x16x32_bf16 v[110:113], v[244:247], v[216:219], v[110:113]
	v_mfma_f32_16x16x32_bf16 v[114:117], v[248:251], v[216:219], v[114:117]
	v_mfma_f32_16x16x32_bf16 v[118:121], v[156:159], v[216:219], v[118:121]
	v_mfma_f32_16x16x32_bf16 v[122:125], v[240:243], v[220:223], v[122:125]
	v_mfma_f32_16x16x32_bf16 v[126:129], v[244:247], v[220:223], v[126:129]
	v_mfma_f32_16x16x32_bf16 v[130:133], v[248:251], v[220:223], v[130:133]
	v_mfma_f32_16x16x32_bf16 v[134:137], v[156:159], v[220:223], v[134:137]
	s_sub_u32 s46, s46, 1
	s_cmp_lg_u32 s46, 0
	s_cbranch_scc1 .Lffn1_kloop
	s_waitcnt vmcnt(6)
	s_barrier
; #define BLOAD(A_, B_, kt) do { _Pragma("unroll") for (int i = 0; i < 4; ++i) { \
;     A_[i] = *(const u32x4*)((const char*)Ap + (aoff + (unsigned)(32 * i * lda + (kt) * 64) * 2u)); B_[i] = *(const u32x4*)((const char*)Wt + (woff + (unsigned)(32 * i * K + (kt) * 64) * 2u)); } } while (0)
; #define BLOAD(A_, B_, kt) do { _Pragma("unroll") for (int i = 0; i < 4; ++i) { \
;     A_[i] = *(const u32x4*)((const char*)Ap + (aoff + (unsigned)(32 * i * lda + (kt) * 64) * 2u)); B_[i] = *(const u32x4*)((const char*)Wt + (woff + (unsigned)(32 * i * K + (kt) * 64) * 2u)); } } while (0)
; #define BSTORE(A_, B_, buf) do { _Pragma("unroll") for (int i = 0; i < 4; ++i) { \
;     *(u32x4*)&As[(buf) * GBUF + (srow + 32 * i) * LDT + sc8] = A_[i]; \
;     *(u32x4*)&Bs[(buf) * GBUF + (srow + 32 * i) * LDT + sc8] = B_[i]; } } while (0)
; template <int NK>
; DI void gemm_run(PF& pf, const u16* __restrict__ Ap, int lda, const u16* __restrict__ Wt, f32x16 (&acc)[2][2], char* smem) {
;     ...
; #pragma unroll
;   for (int kt = 0; kt < nk; kt += 2) {
;     BCOMP(0);
;     BSTORE(pf.a1, pf.b1, 1);
;     if (kt + 3 < nk) BLOAD(pf.a1, pf.b1, kt + 3);
;     __syncthreads();
;     BCOMP(1);
;     if (kt + 2 < nk) { BSTORE(pf.a0, pf.b0, 0); if (kt + 4 < nk) BLOAD(pf.a0, pf.b0, kt + 4); }
;     __syncthreads();
;   }
	ds_read_b128 v[208:211], v138 offset:0
	ds_read_b128 v[224:227], v140 offset:0
	ds_read_b128 v[228:231], v140 offset:1024
	ds_read_b128 v[232:235], v140 offset:2048
	ds_read_b128 v[236:239], v140 offset:3072
	ds_read_b128 v[212:215], v138 offset:1024
	ds_read_b128 v[216:219], v138 offset:2048
	ds_read_b128 v[220:223], v138 offset:3072
	ds_read_b128 v[240:243], v140 offset:8192
	ds_read_b128 v[244:247], v140 offset:9216
	ds_read_b128 v[248:251], v140 offset:10240
	ds_read_b128 v[156:159], v140 offset:11264
	s_waitcnt lgkmcnt(10)
	v_mfma_f32_16x16x32_bf16 v[2:5], v[224:227], v[208:211], v[2:5]
	s_waitcnt lgkmcnt(9)
	v_mfma_f32_16x16x32_bf16 v[6:9], v[228:231], v[208:211], v[6:9]
	s_waitcnt lgkmcnt(8)
	v_mfma_f32_16x16x32_bf16 v[10:13], v[232:235], v[208:211], v[10:13]
	s_waitcnt lgkmcnt(7)
	v_mfma_f32_16x16x32_bf16 v[14:17], v[236:239], v[208:211], v[14:17]
	s_waitcnt lgkmcnt(6)
	v_mfma_f32_16x16x32_bf16 v[18:21], v[224:227], v[212:215], v[18:21]
	v_mfma_f32_16x16x32_bf16 v[22:25], v[228:231], v[212:215], v[22:25]
	v_mfma_f32_16x16x32_bf16 v[26:29], v[232:235], v[212:215], v[26:29]
	v_mfma_f32_16x16x32_bf16 v[30:33], v[236:239], v[212:215], v[30:33]
	s_waitcnt lgkmcnt(5)
	v_mfma_f32_16x16x32_bf16 v[34:37], v[224:227], v[216:219], v[34:37]
	v_mfma_f32_16x16x32_bf16 v[38:41], v[228:231], v[216:219], v[38:41]
	v_mfma_f32_16x16x32_bf16 v[42:45], v[232:235], v[216:219], v[42:45]
	v_mfma_f32_16x16x32_bf16 v[46:49], v[236:239], v[216:219], v[46:49]
	s_waitcnt lgkmcnt(4)
	v_mfma_f32_16x16x32_bf16 v[50:53], v[224:227], v[220:223], v[50:53]
	v_mfma_f32_16x16x32_bf16 v[54:57], v[228:231], v[220:223], v[54:57]
	v_mfma_f32_16x16x32_bf16 v[58:61], v[232:235], v[220:223], v[58:61]
	v_mfma_f32_16x16x32_bf16 v[62:65], v[236:239], v[220:223], v[62:65]
	s_waitcnt lgkmcnt(3)
	v_mfma_f32_16x16x32_bf16 v[74:77], v[240:243], v[208:211], v[74:77]
	s_waitcnt lgkmcnt(2)
	v_mfma_f32_16x16x32_bf16 v[78:81], v[244:247], v[208:211], v[78:81]
	s_waitcnt lgkmcnt(1)
	v_mfma_f32_16x16x32_bf16 v[82:85], v[248:251], v[208:211], v[82:85]
	s_waitcnt lgkmcnt(0)
	v_mfma_f32_16x16x32_bf16 v[86:89], v[156:159], v[208:211], v[86:89]
	v_mfma_f32_16x16x32_bf16 v[90:93], v[240:243], v[212:215], v[90:93]
	v_mfma_f32_16x16x32_bf16 v[94:97], v[244:247], v[212:215], v[94:97]
	v_mfma_f32_16x16x32_bf16 v[98:101], v[248:251], v[212:215], v[98:101]
	v_mfma_f32_16x16x32_bf16 v[102:105], v[156:159], v[212:215], v[102:105]
	v_mfma_f32_16x16x32_bf16 v[106:109], v[240:243], v[216:219], v[106:109]
	v_mfma_f32_16x16x32_bf16 v[110:113], v[244:247], v[216:219], v[110:113]
	v_mfma_f32_16x16x32_bf16 v[114:117], v[248:251], v[216:219], v[114:117]
	v_mfma_f32_16x16x32_bf16 v[118:121], v[156:159], v[216:219], v[118:121]
	v_mfma_f32_16x16x32_bf16 v[122:125], v[240:243], v[220:223], v[122:125]
	v_mfma_f32_16x16x32_bf16 v[126:129], v[244:247], v[220:223], v[126:129]
	v_mfma_f32_16x16x32_bf16 v[130:133], v[248:251], v[220:223], v[130:133]
	v_mfma_f32_16x16x32_bf16 v[134:137], v[156:159], v[220:223], v[134:137]
	s_waitcnt vmcnt(0)
	s_barrier
	ds_read_b128 v[208:211], v138 offset:24576
	ds_read_b128 v[224:227], v140 offset:24576
	ds_read_b128 v[228:231], v140 offset:25600
	ds_read_b128 v[232:235], v140 offset:26624
	ds_read_b128 v[236:239], v140 offset:27648
	ds_read_b128 v[212:215], v138 offset:25600
	ds_read_b128 v[216:219], v138 offset:26624
	ds_read_b128 v[220:223], v138 offset:27648
	ds_read_b128 v[240:243], v140 offset:32768
	ds_read_b128 v[244:247], v140 offset:33792
	ds_read_b128 v[248:251], v140 offset:34816
	ds_read_b128 v[156:159], v140 offset:35840
	s_waitcnt lgkmcnt(10)
	v_mfma_f32_16x16x32_bf16 v[2:5], v[224:227], v[208:211], v[2:5]
	s_waitcnt lgkmcnt(9)
	v_mfma_f32_16x16x32_bf16 v[6:9], v[228:231], v[208:211], v[6:9]
	s_waitcnt lgkmcnt(8)
	v_mfma_f32_16x16x32_bf16 v[10:13], v[232:235], v[208:211], v[10:13]
	s_waitcnt lgkmcnt(7)
	v_mfma_f32_16x16x32_bf16 v[14:17], v[236:239], v[208:211], v[14:17]
	s_waitcnt lgkmcnt(6)
	v_mfma_f32_16x16x32_bf16 v[18:21], v[224:227], v[212:215], v[18:21]
	v_mfma_f32_16x16x32_bf16 v[22:25], v[228:231], v[212:215], v[22:25]
	v_mfma_f32_16x16x32_bf16 v[26:29], v[232:235], v[212:215], v[26:29]
	v_mfma_f32_16x16x32_bf16 v[30:33], v[236:239], v[212:215], v[30:33]
	s_waitcnt lgkmcnt(5)
	v_mfma_f32_16x16x32_bf16 v[34:37], v[224:227], v[216:219], v[34:37]
	v_mfma_f32_16x16x32_bf16 v[38:41], v[228:231], v[216:219], v[38:41]
	v_mfma_f32_16x16x32_bf16 v[42:45], v[232:235], v[216:219], v[42:45]
	v_mfma_f32_16x16x32_bf16 v[46:49], v[236:239], v[216:219], v[46:49]
	s_waitcnt lgkmcnt(4)
	v_mfma_f32_16x16x32_bf16 v[50:53], v[224:227], v[220:223], v[50:53]
	v_mfma_f32_16x16x32_bf16 v[54:57], v[228:231], v[220:223], v[54:57]
	v_mfma_f32_16x16x32_bf16 v[58:61], v[232:235], v[220:223], v[58:61]
	v_mfma_f32_16x16x32_bf16 v[62:65], v[236:239], v[220:223], v[62:65]
	s_waitcnt lgkmcnt(3)
	v_mfma_f32_16x16x32_bf16 v[74:77], v[240:243], v[208:211], v[74:77]
	s_waitcnt lgkmcnt(2)
	v_mfma_f32_16x16x32_bf16 v[78:81], v[244:247], v[208:211], v[78:81]
	s_waitcnt lgkmcnt(1)
	v_mfma_f32_16x16x32_bf16 v[82:85], v[248:251], v[208:211], v[82:85]
	s_waitcnt lgkmcnt(0)
	v_mfma_f32_16x16x32_bf16 v[86:89], v[156:159], v[208:211], v[86:89]
	v_mfma_f32_16x16x32_bf16 v[90:93], v[240:243], v[212:215], v[90:93]
	v_mfma_f32_16x16x32_bf16 v[94:97], v[244:247], v[212:215], v[94:97]
	v_mfma_f32_16x16x32_bf16 v[98:101], v[248:251], v[212:215], v[98:101]
	v_mfma_f32_16x16x32_bf16 v[102:105], v[156:159], v[212:215], v[102:105]
	v_mfma_f32_16x16x32_bf16 v[106:109], v[240:243], v[216:219], v[106:109]
	v_mfma_f32_16x16x32_bf16 v[110:113], v[244:247], v[216:219], v[110:113]
	v_mfma_f32_16x16x32_bf16 v[114:117], v[248:251], v[216:219], v[114:117]
	v_mfma_f32_16x16x32_bf16 v[118:121], v[156:159], v[216:219], v[118:121]
	v_mfma_f32_16x16x32_bf16 v[122:125], v[240:243], v[220:223], v[122:125]
	v_mfma_f32_16x16x32_bf16 v[126:129], v[244:247], v[220:223], v[126:129]
	v_mfma_f32_16x16x32_bf16 v[130:133], v[248:251], v[220:223], v[130:133]
	v_mfma_f32_16x16x32_bf16 v[134:137], v[156:159], v[220:223], v[134:137]
	s_barrier

; #define BLOAD(A_, B_, kt) do { _Pragma("unroll") for (int i = 0; i < 4; ++i) { \
;     A_[i] = *(const u32x4*)((const char*)Ap + (aoff + (unsigned)(32 * i * lda + (kt) * 64) * 2u)); B_[i] = *(const u32x4*)((const char*)Wt + (woff + (unsigned)(32 * i * K + (kt) * 64) * 2u)); } } while (0)
; #define BLOAD(A_, B_, kt) do { _Pragma("unroll") for (int i = 0; i < 4; ++i) { \
;     A_[i] = *(const u32x4*)((const char*)Ap + (aoff + (unsigned)(32 * i * lda + (kt) * 64) * 2u)); B_[i] = *(const u32x4*)((const char*)Wt + (woff + (unsigned)(32 * i * K + (kt) * 64) * 2u)); } } while (0)
; #define BSTORE(A_, B_, buf) do { _Pragma("unroll") for (int i = 0; i < 4; ++i) { \
;     *(u32x4*)&As[(buf) * GBUF + (srow + 32 * i) * LDT + sc8] = A_[i]; \
;     *(u32x4*)&Bs[(buf) * GBUF + (srow + 32 * i) * LDT + sc8] = B_[i]; } } while (0)
; template <int NK>
; DI void gemm_run(PF& pf, const u16* __restrict__ Ap, int lda, const u16* __restrict__ Wt, f32x16 (&acc)[2][2], char* smem) {
;     ...
; #pragma unroll
;   for (int kt = 0; kt < nk; kt += 2) {
;     BCOMP(0);
;     BSTORE(pf.a1, pf.b1, 1);
;     if (kt + 3 < nk) BLOAD(pf.a1, pf.b1, kt + 3);
;     __syncthreads();
;     BCOMP(1);
;     if (kt + 2 < nk) { BSTORE(pf.a0, pf.b0, 0); if (kt + 4 < nk) BLOAD(pf.a0, pf.b0, kt + 4); }
;     __syncthreads();
;   }
.Lout_kloop:
	s_waitcnt vmcnt(6)
	s_barrier
	ds_read_b128 v[224:227], v126 offset:0
	ds_read_b128 v[240:243], v128 offset:0
	ds_read_b128 v[244:247], v128 offset:1024
	ds_read_b128 v[248:251], v128 offset:2048
	ds_read_b128 v[156:159], v128 offset:3072
	ds_read_b128 v[228:231], v126 offset:1024
	ds_read_b128 v[232:235], v126 offset:2048
	ds_read_b128 v[236:239], v126 offset:3072
	ds_read_b128 v[160:163], v128 offset:8192
	ds_read_b128 v[164:167], v128 offset:9216
	ds_read_b128 v[168:171], v128 offset:10240
	ds_read_b128 v[122:125], v128 offset:11264
	s_waitcnt lgkmcnt(10)
	v_mfma_f32_16x16x32_bf16 v[2:5], v[240:243], v[224:227], v[2:5]
	s_waitcnt lgkmcnt(9)
	v_mfma_f32_16x16x32_bf16 v[6:9], v[244:247], v[224:227], v[6:9]
	s_waitcnt lgkmcnt(8)
	v_mfma_f32_16x16x32_bf16 v[10:13], v[248:251], v[224:227], v[10:13]
	s_waitcnt lgkmcnt(7)
	v_mfma_f32_16x16x32_bf16 v[14:17], v[156:159], v[224:227], v[14:17]
	s_waitcnt lgkmcnt(6)
	v_mfma_f32_16x16x32_bf16 v[18:21], v[240:243], v[228:231], v[18:21]
	v_mfma_f32_16x16x32_bf16 v[22:25], v[244:247], v[228:231], v[22:25]
	v_mfma_f32_16x16x32_bf16 v[26:29], v[248:251], v[228:231], v[26:29]
	v_mfma_f32_16x16x32_bf16 v[30:33], v[156:159], v[228:231], v[30:33]
	s_waitcnt lgkmcnt(5)
	v_mfma_f32_16x16x32_bf16 v[34:37], v[240:243], v[232:235], v[34:37]
	v_mfma_f32_16x16x32_bf16 v[38:41], v[244:247], v[232:235], v[38:41]
	v_mfma_f32_16x16x32_bf16 v[42:45], v[248:251], v[232:235], v[42:45]
	v_mfma_f32_16x16x32_bf16 v[46:49], v[156:159], v[232:235], v[46:49]
	s_waitcnt lgkmcnt(4)
	v_mfma_f32_16x16x32_bf16 v[50:53], v[240:243], v[236:239], v[50:53]
	v_mfma_f32_16x16x32_bf16 v[54:57], v[244:247], v[236:239], v[54:57]
	v_mfma_f32_16x16x32_bf16 v[58:61], v[248:251], v[236:239], v[58:61]
	v_mfma_f32_16x16x32_bf16 v[62:65], v[156:159], v[236:239], v[62:65]
	s_add_u32 m0, s42, 0xc000
	s_add_u32 s28, s28, 0x100000
	s_addc_u32 s29, s29, 0
	global_load_lds_dwordx4 v143, s[28:29]
	global_load_lds_dwordx4 v144, s[28:29] offset:1024
	s_add_u32 m0, s43, 0xc000
	s_add_u32 s30, s30, 0x10000
	s_addc_u32 s31, s31, 0
	global_load_lds_dwordx4 v145, s[30:31]
	global_load_lds_dwordx4 v146, s[30:31] offset:1024
	global_load_lds_dwordx4 v147, s[30:31] offset:2048
	global_load_lds_dwordx4 v148, s[30:31] offset:3072
	s_waitcnt lgkmcnt(3)
	v_mfma_f32_16x16x32_bf16 v[74:77], v[160:163], v[224:227], v[74:77]
	s_waitcnt lgkmcnt(2)
	v_mfma_f32_16x16x32_bf16 v[78:81], v[164:167], v[224:227], v[78:81]
	s_waitcnt lgkmcnt(1)
	v_mfma_f32_16x16x32_bf16 v[82:85], v[168:171], v[224:227], v[82:85]
	s_waitcnt lgkmcnt(0)
	v_mfma_f32_16x16x32_bf16 v[86:89], v[122:125], v[224:227], v[86:89]
	v_mfma_f32_16x16x32_bf16 v[90:93], v[160:163], v[228:231], v[90:93]
	v_mfma_f32_16x16x32_bf16 v[94:97], v[164:167], v[228:231], v[94:97]
	v_mfma_f32_16x16x32_bf16 v[98:101], v[168:171], v[228:231], v[98:101]
	v_mfma_f32_16x16x32_bf16 v[102:105], v[122:125], v[228:231], v[102:105]
	v_mfma_f32_16x16x32_bf16 v[106:109], v[160:163], v[232:235], v[106:109]
	v_mfma_f32_16x16x32_bf16 v[110:113], v[164:167], v[232:235], v[110:113]
	v_mfma_f32_16x16x32_bf16 v[114:117], v[168:171], v[232:235], v[114:117]
	v_mfma_f32_16x16x32_bf16 v[118:121], v[122:125], v[232:235], v[118:121]
	v_mfma_f32_16x16x32_bf16 v[208:211], v[160:163], v[236:239], v[208:211]
	v_mfma_f32_16x16x32_bf16 v[212:215], v[164:167], v[236:239], v[212:215]
	v_mfma_f32_16x16x32_bf16 v[216:219], v[168:171], v[236:239], v[216:219]
	v_mfma_f32_16x16x32_bf16 v[220:223], v[122:125], v[236:239], v[220:223]
	s_waitcnt vmcnt(6)
	s_barrier
	ds_read_b128 v[224:227], v126 offset:24576
	ds_read_b128 v[240:243], v128 offset:24576
	ds_read_b128 v[244:247], v128 offset:25600
	ds_read_b128 v[248:251], v128 offset:26624
	ds_read_b128 v[156:159], v128 offset:27648
	ds_read_b128 v[228:231], v126 offset:25600
	ds_read_b128 v[232:235], v126 offset:26624
	ds_read_b128 v[236:239], v126 offset:27648
	ds_read_b128 v[160:163], v128 offset:32768
	ds_read_b128 v[164:167], v128 offset:33792
	ds_read_b128 v[168:171], v128 offset:34816
	ds_read_b128 v[122:125], v128 offset:35840
	s_waitcnt lgkmcnt(10)
	v_mfma_f32_16x16x32_bf16 v[2:5], v[240:243], v[224:227], v[2:5]
	s_waitcnt lgkmcnt(9)
	v_mfma_f32_16x16x32_bf16 v[6:9], v[244:247], v[224:227], v[6:9]
	s_waitcnt lgkmcnt(8)
	v_mfma_f32_16x16x32_bf16 v[10:13], v[248:251], v[224:227], v[10:13]
	s_waitcnt lgkmcnt(7)
	v_mfma_f32_16x16x32_bf16 v[14:17], v[156:159], v[224:227], v[14:17]
	s_waitcnt lgkmcnt(6)
	v_mfma_f32_16x16x32_bf16 v[18:21], v[240:243], v[228:231], v[18:21]
	v_mfma_f32_16x16x32_bf16 v[22:25], v[244:247], v[228:231], v[22:25]
	v_mfma_f32_16x16x32_bf16 v[26:29], v[248:251], v[228:231], v[26:29]
	v_mfma_f32_16x16x32_bf16 v[30:33], v[156:159], v[228:231], v[30:33]
	s_waitcnt lgkmcnt(5)
	v_mfma_f32_16x16x32_bf16 v[34:37], v[240:243], v[232:235], v[34:37]
	v_mfma_f32_16x16x32_bf16 v[38:41], v[244:247], v[232:235], v[38:41]
	v_mfma_f32_16x16x32_bf16 v[42:45], v[248:251], v[232:235], v[42:45]
	v_mfma_f32_16x16x32_bf16 v[46:49], v[156:159], v[232:235], v[46:49]
	s_waitcnt lgkmcnt(4)
	v_mfma_f32_16x16x32_bf16 v[50:53], v[240:243], v[236:239], v[50:53]
	v_mfma_f32_16x16x32_bf16 v[54:57], v[244:247], v[236:239], v[54:57]
	v_mfma_f32_16x16x32_bf16 v[58:61], v[248:251], v[236:239], v[58:61]
	v_mfma_f32_16x16x32_bf16 v[62:65], v[156:159], v[236:239], v[62:65]
	s_add_u32 m0, s42, 0x0
	s_add_u32 s28, s28, 0x100000
	s_addc_u32 s29, s29, 0
	global_load_lds_dwordx4 v143, s[28:29]
	global_load_lds_dwordx4 v144, s[28:29] offset:1024
	s_add_u32 m0, s43, 0x0
	s_add_u32 s30, s30, 0x10000
	s_addc_u32 s31, s31, 0
	global_load_lds_dwordx4 v145, s[30:31]
	global_load_lds_dwordx4 v146, s[30:31] offset:1024
	global_load_lds_dwordx4 v147, s[30:31] offset:2048
	global_load_lds_dwordx4 v148, s[30:31] offset:3072
	s_waitcnt lgkmcnt(3)
	v_mfma_f32_16x16x32_bf16 v[74:77], v[160:163], v[224:227], v[74:77]
	s_waitcnt lgkmcnt(2)
	v_mfma_f32_16x16x32_bf16 v[78:81], v[164:167], v[224:227], v[78:81]
	s_waitcnt lgkmcnt(1)
	v_mfma_f32_16x16x32_bf16 v[82:85], v[168:171], v[224:227], v[82:85]
	s_waitcnt lgkmcnt(0)
	v_mfma_f32_16x16x32_bf16 v[86:89], v[122:125], v[224:227], v[86:89]
	v_mfma_f32_16x16x32_bf16 v[90:93], v[160:163], v[228:231], v[90:93]
	v_mfma_f32_16x16x32_bf16 v[94:97], v[164:167], v[228:231], v[94:97]
	v_mfma_f32_16x16x32_bf16 v[98:101], v[168:171], v[228:231], v[98:101]
	v_mfma_f32_16x16x32_bf16 v[102:105], v[122:125], v[228:231], v[102:105]
	v_mfma_f32_16x16x32_bf16 v[106:109], v[160:163], v[232:235], v[106:109]
	v_mfma_f32_16x16x32_bf16 v[110:113], v[164:167], v[232:235], v[110:113]
	v_mfma_f32_16x16x32_bf16 v[114:117], v[168:171], v[232:235], v[114:117]
	v_mfma_f32_16x16x32_bf16 v[118:121], v[122:125], v[232:235], v[118:121]
	v_mfma_f32_16x16x32_bf16 v[208:211], v[160:163], v[236:239], v[208:211]
	v_mfma_f32_16x16x32_bf16 v[212:215], v[164:167], v[236:239], v[212:215]
	v_mfma_f32_16x16x32_bf16 v[216:219], v[168:171], v[236:239], v[216:219]
	v_mfma_f32_16x16x32_bf16 v[220:223], v[122:125], v[236:239], v[220:223]
	s_waitcnt vmcnt(6)
	s_barrier
; #define BLOAD(A_, B_, kt) do { _Pragma("unroll") for (int i = 0; i < 4; ++i) { \
;     A_[i] = *(const u32x4*)((const char*)Ap + (aoff + (unsigned)(32 * i * lda + (kt) * 64) * 2u)); B_[i] = *(const u32x4*)((const char*)Wt + (woff + (unsigned)(32 * i * K + (kt) * 64) * 2u)); } } while (0)
; #define BLOAD(A_, B_, kt) do { _Pragma("unroll") for (int i = 0; i < 4; ++i) { \
;     A_[i] = *(const u32x4*)((const char*)Ap + (aoff + (unsigned)(32 * i * lda + (kt) * 64) * 2u)); B_[i] = *(const u32x4*)((const char*)Wt + (woff + (unsigned)(32 * i * K + (kt) * 64) * 2u)); } } while (0)
; #define BSTORE(A_, B_, buf) do { _Pragma("unroll") for (int i = 0; i < 4; ++i) { \
;     *(u32x4*)&As[(buf) * GBUF + (srow + 32 * i) * LDT + sc8] = A_[i]; \
;     *(u32x4*)&Bs[(buf) * GBUF + (srow + 32 * i) * LDT + sc8] = B_[i]; } } while (0)
; template <int NK>
; DI void gemm_run(PF& pf, const u16* __restrict__ Ap, int lda, const u16* __restrict__ Wt, f32x16 (&acc)[2][2], char* smem) {
;     ...
; #pragma unroll
;   for (int kt = 0; kt < nk; kt += 2) {
;     BCOMP(0);
;     BSTORE(pf.a1, pf.b1, 1);
;     if (kt + 3 < nk) BLOAD(pf.a1, pf.b1, kt + 3);
;     __syncthreads();
;     BCOMP(1);
;     if (kt + 2 < nk) { BSTORE(pf.a0, pf.b0, 0); if (kt + 4 < nk) BLOAD(pf.a0, pf.b0, kt + 4); }
;     __syncthreads();
;   }
	ds_read_b128 v[224:227], v126 offset:49152
	ds_read_b128 v[240:243], v128 offset:49152
	ds_read_b128 v[244:247], v128 offset:50176
	ds_read_b128 v[248:251], v128 offset:51200
	ds_read_b128 v[156:159], v128 offset:52224
	ds_read_b128 v[228:231], v126 offset:50176
	ds_read_b128 v[232:235], v126 offset:51200
	ds_read_b128 v[236:239], v126 offset:52224
	ds_read_b128 v[160:163], v128 offset:57344
	ds_read_b128 v[164:167], v128 offset:58368
	ds_read_b128 v[168:171], v128 offset:59392
	ds_read_b128 v[122:125], v128 offset:60416
	s_waitcnt lgkmcnt(10)
	v_mfma_f32_16x16x32_bf16 v[2:5], v[240:243], v[224:227], v[2:5]
	s_waitcnt lgkmcnt(9)
	v_mfma_f32_16x16x32_bf16 v[6:9], v[244:247], v[224:227], v[6:9]
	s_waitcnt lgkmcnt(8)
	v_mfma_f32_16x16x32_bf16 v[10:13], v[248:251], v[224:227], v[10:13]
	s_waitcnt lgkmcnt(7)
	v_mfma_f32_16x16x32_bf16 v[14:17], v[156:159], v[224:227], v[14:17]
	s_waitcnt lgkmcnt(6)
	v_mfma_f32_16x16x32_bf16 v[18:21], v[240:243], v[228:231], v[18:21]
	v_mfma_f32_16x16x32_bf16 v[22:25], v[244:247], v[228:231], v[22:25]
	v_mfma_f32_16x16x32_bf16 v[26:29], v[248:251], v[228:231], v[26:29]
	v_mfma_f32_16x16x32_bf16 v[30:33], v[156:159], v[228:231], v[30:33]
	s_waitcnt lgkmcnt(5)
	v_mfma_f32_16x16x32_bf16 v[34:37], v[240:243], v[232:235], v[34:37]
	v_mfma_f32_16x16x32_bf16 v[38:41], v[244:247], v[232:235], v[38:41]
	v_mfma_f32_16x16x32_bf16 v[42:45], v[248:251], v[232:235], v[42:45]
	v_mfma_f32_16x16x32_bf16 v[46:49], v[156:159], v[232:235], v[46:49]
	s_waitcnt lgkmcnt(4)
	v_mfma_f32_16x16x32_bf16 v[50:53], v[240:243], v[236:239], v[50:53]
	v_mfma_f32_16x16x32_bf16 v[54:57], v[244:247], v[236:239], v[54:57]
	v_mfma_f32_16x16x32_bf16 v[58:61], v[248:251], v[236:239], v[58:61]
	v_mfma_f32_16x16x32_bf16 v[62:65], v[156:159], v[236:239], v[62:65]
	s_add_u32 m0, s42, 0x6000
	s_add_u32 s28, s28, 0x100000
	s_addc_u32 s29, s29, 0
	global_load_lds_dwordx4 v143, s[28:29]
	global_load_lds_dwordx4 v144, s[28:29] offset:1024
	s_add_u32 m0, s43, 0x6000
	s_add_u32 s30, s30, 0x10000
	s_addc_u32 s31, s31, 0
	global_load_lds_dwordx4 v145, s[30:31]
	global_load_lds_dwordx4 v146, s[30:31] offset:1024
	global_load_lds_dwordx4 v147, s[30:31] offset:2048
	global_load_lds_dwordx4 v148, s[30:31] offset:3072
	s_waitcnt lgkmcnt(3)
	v_mfma_f32_16x16x32_bf16 v[74:77], v[160:163], v[224:227], v[74:77]
	s_waitcnt lgkmcnt(2)
	v_mfma_f32_16x16x32_bf16 v[78:81], v[164:167], v[224:227], v[78:81]
	s_waitcnt lgkmcnt(1)
	v_mfma_f32_16x16x32_bf16 v[82:85], v[168:171], v[224:227], v[82:85]
	s_waitcnt lgkmcnt(0)
	v_mfma_f32_16x16x32_bf16 v[86:89], v[122:125], v[224:227], v[86:89]
	v_mfma_f32_16x16x32_bf16 v[90:93], v[160:163], v[228:231], v[90:93]
	v_mfma_f32_16x16x32_bf16 v[94:97], v[164:167], v[228:231], v[94:97]
	v_mfma_f32_16x16x32_bf16 v[98:101], v[168:171], v[228:231], v[98:101]
	v_mfma_f32_16x16x32_bf16 v[102:105], v[122:125], v[228:231], v[102:105]
	v_mfma_f32_16x16x32_bf16 v[106:109], v[160:163], v[232:235], v[106:109]
	v_mfma_f32_16x16x32_bf16 v[110:113], v[164:167], v[232:235], v[110:113]
	v_mfma_f32_16x16x32_bf16 v[114:117], v[168:171], v[232:235], v[114:117]
	v_mfma_f32_16x16x32_bf16 v[118:121], v[122:125], v[232:235], v[118:121]
	v_mfma_f32_16x16x32_bf16 v[208:211], v[160:163], v[236:239], v[208:211]
	v_mfma_f32_16x16x32_bf16 v[212:215], v[164:167], v[236:239], v[212:215]
	v_mfma_f32_16x16x32_bf16 v[216:219], v[168:171], v[236:239], v[216:219]
	v_mfma_f32_16x16x32_bf16 v[220:223], v[122:125], v[236:239], v[220:223]
	s_sub_u32 s46, s46, 1
	s_cmp_lg_u32 s46, 0
	s_cbranch_scc1 .Lout_kloop
	s_waitcnt vmcnt(6)
	s_barrier
	ds_read_b128 v[224:227], v126 offset:0
	ds_read_b128 v[240:243], v128 offset:0
	ds_read_b128 v[244:247], v128 offset:1024
	ds_read_b128 v[248:251], v128 offset:2048
	ds_read_b128 v[156:159], v128 offset:3072
	ds_read_b128 v[228:231], v126 offset:1024
	ds_read_b128 v[232:235], v126 offset:2048
	ds_read_b128 v[236:239], v126 offset:3072
	ds_read_b128 v[160:163], v128 offset:8192
	ds_read_b128 v[164:167], v128 offset:9216
	ds_read_b128 v[168:171], v128 offset:10240
	ds_read_b128 v[122:125], v128 offset:11264
	s_waitcnt lgkmcnt(10)
	v_mfma_f32_16x16x32_bf16 v[2:5], v[240:243], v[224:227], v[2:5]
	s_waitcnt lgkmcnt(9)
	v_mfma_f32_16x16x32_bf16 v[6:9], v[244:247], v[224:227], v[6:9]
	s_waitcnt lgkmcnt(8)
	v_mfma_f32_16x16x32_bf16 v[10:13], v[248:251], v[224:227], v[10:13]
	s_waitcnt lgkmcnt(7)
	v_mfma_f32_16x16x32_bf16 v[14:17], v[156:159], v[224:227], v[14:17]
	s_waitcnt lgkmcnt(6)
	v_mfma_f32_16x16x32_bf16 v[18:21], v[240:243], v[228:231], v[18:21]
	v_mfma_f32_16x16x32_bf16 v[22:25], v[244:247], v[228:231], v[22:25]
	v_mfma_f32_16x16x32_bf16 v[26:29], v[248:251], v[228:231], v[26:29]
	v_mfma_f32_16x16x32_bf16 v[30:33], v[156:159], v[228:231], v[30:33]
	s_waitcnt lgkmcnt(5)
	v_mfma_f32_16x16x32_bf16 v[34:37], v[240:243], v[232:235], v[34:37]
	v_mfma_f32_16x16x32_bf16 v[38:41], v[244:247], v[232:235], v[38:41]
	v_mfma_f32_16x16x32_bf16 v[42:45], v[248:251], v[232:235], v[42:45]
	v_mfma_f32_16x16x32_bf16 v[46:49], v[156:159], v[232:235], v[46:49]
	s_waitcnt lgkmcnt(4)
	v_mfma_f32_16x16x32_bf16 v[50:53], v[240:243], v[236:239], v[50:53]
	v_mfma_f32_16x16x32_bf16 v[54:57], v[244:247], v[236:239], v[54:57]
	v_mfma_f32_16x16x32_bf16 v[58:61], v[248:251], v[236:239], v[58:61]
	v_mfma_f32_16x16x32_bf16 v[62:65], v[156:159], v[236:239], v[62:65]
	s_waitcnt lgkmcnt(3)
	v_mfma_f32_16x16x32_bf16 v[74:77], v[160:163], v[224:227], v[74:77]
	s_waitcnt lgkmcnt(2)
	v_mfma_f32_16x16x32_bf16 v[78:81], v[164:167], v[224:227], v[78:81]
	s_waitcnt lgkmcnt(1)
	v_mfma_f32_16x16x32_bf16 v[82:85], v[168:171], v[224:227], v[82:85]
	s_waitcnt lgkmcnt(0)
	v_mfma_f32_16x16x32_bf16 v[86:89], v[122:125], v[224:227], v[86:89]
	v_mfma_f32_16x16x32_bf16 v[90:93], v[160:163], v[228:231], v[90:93]
	v_mfma_f32_16x16x32_bf16 v[94:97], v[164:167], v[228:231], v[94:97]
	v_mfma_f32_16x16x32_bf16 v[98:101], v[168:171], v[228:231], v[98:101]
	v_mfma_f32_16x16x32_bf16 v[102:105], v[122:125], v[228:231], v[102:105]
	v_mfma_f32_16x16x32_bf16 v[106:109], v[160:163], v[232:235], v[106:109]
	v_mfma_f32_16x16x32_bf16 v[110:113], v[164:167], v[232:235], v[110:113]
	v_mfma_f32_16x16x32_bf16 v[114:117], v[168:171], v[232:235], v[114:117]
	v_mfma_f32_16x16x32_bf16 v[118:121], v[122:125], v[232:235], v[118:121]
	v_mfma_f32_16x16x32_bf16 v[208:211], v[160:163], v[236:239], v[208:211]
	v_mfma_f32_16x16x32_bf16 v[212:215], v[164:167], v[236:239], v[212:215]
	v_mfma_f32_16x16x32_bf16 v[216:219], v[168:171], v[236:239], v[216:219]
	v_mfma_f32_16x16x32_bf16 v[220:223], v[122:125], v[236:239], v[220:223]
	s_waitcnt vmcnt(0)
	s_barrier
; DI void tile_outproj(const Params& p, int l, const Chunk& ck, int tile, int next, PF& pf, char* smem) {
;     ...
;   { const u16* Ap; const u16* Wt; outproj_ptrs(p, l, tile, Ap, Wt); gemm_run<16>(pf, Ap, 1024, Wt, acc, smem); }
;   if (next >= 0) { const u16* An; const u16* Wn; outproj_ptrs(p, l, next, An, Wn); gemm_issue(pf, An, 1024, Wn, 1024); }
;   acc_to_cs(acc, Cs);
;   const int row = tid >> 1, half = tid & 1; float ssq = 0.f;
;   u16* xb = (u16*)(p.ws + OFF_XB) + (size_t)(m0 + row) * 1024 + n0 + half * 64;
; #pragma unroll
;   for (int c8 = 0; c8 < 8; ++c8) {
;     float v[8], x[8]; cs_ld8(Cs, row, half * 64 + c8 * 8, v); unpack8(*(const u32x4*)(xb + c8 * 8), x);
	ds_read_b128 v[224:227], v126 offset:24576
	ds_read_b128 v[240:243], v128 offset:24576
	ds_read_b128 v[244:247], v128 offset:25600
	ds_read_b128 v[248:251], v128 offset:26624
	ds_read_b128 v[156:159], v128 offset:27648
	ds_read_b128 v[228:231], v126 offset:25600
	ds_read_b128 v[232:235], v126 offset:26624
	ds_read_b128 v[236:239], v126 offset:27648
	ds_read_b128 v[160:163], v128 offset:32768
	ds_read_b128 v[164:167], v128 offset:33792
	ds_read_b128 v[168:171], v128 offset:34816
	ds_read_b128 v[122:125], v128 offset:35840
	s_waitcnt lgkmcnt(10)
	v_mfma_f32_16x16x32_bf16 v[2:5], v[240:243], v[224:227], v[2:5]
	s_waitcnt lgkmcnt(9)
	v_mfma_f32_16x16x32_bf16 v[6:9], v[244:247], v[224:227], v[6:9]
	s_waitcnt lgkmcnt(8)
	v_mfma_f32_16x16x32_bf16 v[10:13], v[248:251], v[224:227], v[10:13]
	s_waitcnt lgkmcnt(7)
	v_mfma_f32_16x16x32_bf16 v[14:17], v[156:159], v[224:227], v[14:17]
	s_waitcnt lgkmcnt(6)
	v_mfma_f32_16x16x32_bf16 v[18:21], v[240:243], v[228:231], v[18:21]
	v_mfma_f32_16x16x32_bf16 v[22:25], v[244:247], v[228:231], v[22:25]
	v_mfma_f32_16x16x32_bf16 v[26:29], v[248:251], v[228:231], v[26:29]
	v_mfma_f32_16x16x32_bf16 v[30:33], v[156:159], v[228:231], v[30:33]
	s_waitcnt lgkmcnt(5)
	v_mfma_f32_16x16x32_bf16 v[34:37], v[240:243], v[232:235], v[34:37]
	v_mfma_f32_16x16x32_bf16 v[38:41], v[244:247], v[232:235], v[38:41]
	v_mfma_f32_16x16x32_bf16 v[42:45], v[248:251], v[232:235], v[42:45]
	v_mfma_f32_16x16x32_bf16 v[46:49], v[156:159], v[232:235], v[46:49]
	s_waitcnt lgkmcnt(4)
	v_mfma_f32_16x16x32_bf16 v[50:53], v[240:243], v[236:239], v[50:53]
	v_mfma_f32_16x16x32_bf16 v[54:57], v[244:247], v[236:239], v[54:57]
	v_mfma_f32_16x16x32_bf16 v[58:61], v[248:251], v[236:239], v[58:61]
	v_mfma_f32_16x16x32_bf16 v[62:65], v[156:159], v[236:239], v[62:65]
	s_waitcnt lgkmcnt(3)
	v_mfma_f32_16x16x32_bf16 v[74:77], v[160:163], v[224:227], v[74:77]
	s_waitcnt lgkmcnt(2)
	v_mfma_f32_16x16x32_bf16 v[78:81], v[164:167], v[224:227], v[78:81]
	s_waitcnt lgkmcnt(1)
	v_mfma_f32_16x16x32_bf16 v[82:85], v[168:171], v[224:227], v[82:85]
	s_waitcnt lgkmcnt(0)
	v_mfma_f32_16x16x32_bf16 v[86:89], v[122:125], v[224:227], v[86:89]
	v_mfma_f32_16x16x32_bf16 v[90:93], v[160:163], v[228:231], v[90:93]
	v_mfma_f32_16x16x32_bf16 v[94:97], v[164:167], v[228:231], v[94:97]
	v_mfma_f32_16x16x32_bf16 v[98:101], v[168:171], v[228:231], v[98:101]
	v_mfma_f32_16x16x32_bf16 v[102:105], v[122:125], v[228:231], v[102:105]
	v_mfma_f32_16x16x32_bf16 v[106:109], v[160:163], v[232:235], v[106:109]
	v_mfma_f32_16x16x32_bf16 v[110:113], v[164:167], v[232:235], v[110:113]
	v_mfma_f32_16x16x32_bf16 v[114:117], v[168:171], v[232:235], v[114:117]
	v_mfma_f32_16x16x32_bf16 v[118:121], v[122:125], v[232:235], v[118:121]
	v_mfma_f32_16x16x32_bf16 v[208:211], v[160:163], v[236:239], v[208:211]
	v_mfma_f32_16x16x32_bf16 v[212:215], v[164:167], v[236:239], v[212:215]
	v_mfma_f32_16x16x32_bf16 v[216:219], v[168:171], v[236:239], v[216:219]
	v_mfma_f32_16x16x32_bf16 v[220:223], v[122:125], v[236:239], v[220:223]
	s_barrier
	s_and_b32 s0, s40, 0x3f80
	v_and_b32_e32 v160, 63, v172
	v_lshrrev_b32_e32 v161, 6, v172
	v_and_b32_e32 v162, 15, v160
	v_lshrrev_b32_e32 v163, 4, v160
	v_lshrrev_b32_e32 v167, 1, v161
	v_lshl_add_u32 v167, v167, 6, v162
	v_and_b32_e32 v168, 1, v161
	v_lshlrev_b32_e32 v169, 6, v168
	v_lshl_add_u32 v169, v163, 2, v169
	v_add_u32_e32 v169, s26, v169
	v_add_u32_e32 v170, s0, v167
	v_lshlrev_b32_e32 v164, 6, v170
	v_lshl_add_u32 v164, v163, 3, v164
	v_lshrrev_b32_e32 v122, 5, v169
	v_lshl_add_u32 v164, v122, 20, v164
	v_add_u32_e32 v122, 0x100000, v164
	v_lshlrev_b32_e32 v165, 12, v167
	v_lshl_add_u32 v165, v169, 2, v165
	v_lshlrev_b32_e32 v166, 6, v170
	v_lshl_add_u32 v166, v168, 2, v166
	s_lshr_b32 s0, s26, 4
	s_add_u32 s14, s22, s0
	s_addc_u32 s15, s23, 0
	global_load_dwordx2 v[224:225], v164, s[20:21] offset:0
	global_load_dwordx2 v[226:227], v164, s[20:21] offset:32
	global_load_dwordx2 v[228:229], v122, s[20:21] offset:0
	global_load_dwordx2 v[230:231], v122, s[20:21] offset:32
	global_load_dwordx2 v[232:233], v164, s[20:21] offset:1024
	global_load_dwordx2 v[234:235], v164, s[20:21] offset:1056
	global_load_dwordx2 v[236:237], v122, s[20:21] offset:1024
	global_load_dwordx2 v[238:239], v122, s[20:21] offset:1056
	global_load_dwordx2 v[240:241], v164, s[20:21] offset:2048
	global_load_dwordx2 v[242:243], v164, s[20:21] offset:2080
	global_load_dwordx2 v[244:245], v122, s[20:21] offset:2048
	global_load_dwordx2 v[246:247], v122, s[20:21] offset:2080
	global_load_dwordx2 v[248:249], v164, s[20:21] offset:3072
	global_load_dwordx2 v[250:251], v164, s[20:21] offset:3104
	global_load_dwordx2 v[156:157], v122, s[20:21] offset:3072
	global_load_dwordx2 v[158:159], v122, s[20:21] offset:3104
	s_waitcnt vmcnt(0)
; DI u32x4 pack8(const float (&v)[8]) { u32x4 r = {pk2(v[0], v[1]), pk2(v[2], v[3]), pk2(v[4], v[5]), pk2(v[6], v[7])}; return r; }
; DI void tile_outproj(const Params& p, int l, const Chunk& ck, int tile, int next, PF& pf, char* smem) {
;     ...
;   const int row = tid >> 1, half = tid & 1; float ssq = 0.f;
;   u16* xb = (u16*)(p.ws + OFF_XB) + (size_t)(m0 + row) * 1024 + n0 + half * 64;
; #pragma unroll
;   for (int c8 = 0; c8 < 8; ++c8) {
;     float v[8], x[8]; cs_ld8(Cs, row, half * 64 + c8 * 8, v); unpack8(*(const u32x4*)(xb + c8 * 8), x);
; #pragma unroll
;     for (int j = 0; j < 8; ++j) { v[j] += x[j]; ssq += v[j] * v[j]; }
;     *(u32x4*)(xb + c8 * 8) = pack8(v);
;   }
;   ((float*)(p.ws + OFF_PSMID))[(size_t)(m0 + row) * 16 + ni * 2 + half] = ssq;
	v_mov_b32_e32 v171, 0
	v_lshlrev_b32_e32 v167, 16, v224
	v_and_b32_e32 v168, 0xffff0000, v224
	v_lshlrev_b32_e32 v169, 16, v225
	v_and_b32_e32 v170, 0xffff0000, v225
	v_add_f32_e32 v2, v2, v167
	v_add_f32_e32 v3, v3, v168
	v_add_f32_e32 v4, v4, v169
	v_add_f32_e32 v5, v5, v170
	v_fma_f32 v171, v2, v2, v171
	v_fma_f32 v171, v3, v3, v171
	v_fma_f32 v171, v4, v4, v171
	v_fma_f32 v171, v5, v5, v171
	v_cvt_pk_bf16_f32 v2, v2, v3
	v_cvt_pk_bf16_f32 v3, v4, v5
	global_store_dwordx2 v164, v[2:3], s[20:21]
	v_lshlrev_b32_e32 v167, 16, v226
	v_and_b32_e32 v168, 0xffff0000, v226
	v_lshlrev_b32_e32 v169, 16, v227
	v_and_b32_e32 v170, 0xffff0000, v227
	v_add_f32_e32 v6, v6, v167
	v_add_f32_e32 v7, v7, v168
	v_add_f32_e32 v8, v8, v169
	v_add_f32_e32 v9, v9, v170
	v_fma_f32 v171, v6, v6, v171
	v_fma_f32 v171, v7, v7, v171
	v_fma_f32 v171, v8, v8, v171
	v_fma_f32 v171, v9, v9, v171
	v_cvt_pk_bf16_f32 v6, v6, v7
	v_cvt_pk_bf16_f32 v7, v8, v9
	global_store_dwordx2 v164, v[6:7], s[20:21] offset:32
	v_lshlrev_b32_e32 v167, 16, v228
	v_and_b32_e32 v168, 0xffff0000, v228
	v_lshlrev_b32_e32 v169, 16, v229
	v_and_b32_e32 v170, 0xffff0000, v229
	v_add_f32_e32 v10, v10, v167
	v_add_f32_e32 v11, v11, v168
	v_add_f32_e32 v12, v12, v169
	v_add_f32_e32 v13, v13, v170
	v_fma_f32 v171, v10, v10, v171
	v_fma_f32 v171, v11, v11, v171
	v_fma_f32 v171, v12, v12, v171
	v_fma_f32 v171, v13, v13, v171
	v_cvt_pk_bf16_f32 v10, v10, v11
	v_cvt_pk_bf16_f32 v11, v12, v13
	global_store_dwordx2 v122, v[10:11], s[20:21]
	v_lshlrev_b32_e32 v167, 16, v230
	v_and_b32_e32 v168, 0xffff0000, v230
	v_lshlrev_b32_e32 v169, 16, v231
	v_and_b32_e32 v170, 0xffff0000, v231
	v_add_f32_e32 v14, v14, v167
	v_add_f32_e32 v15, v15, v168
	v_add_f32_e32 v16, v16, v169
	v_add_f32_e32 v17, v17, v170
	v_fma_f32 v171, v14, v14, v171
	v_fma_f32 v171, v15, v15, v171
	v_fma_f32 v171, v16, v16, v171
	v_fma_f32 v171, v17, v17, v171
	v_cvt_pk_bf16_f32 v14, v14, v15
	v_cvt_pk_bf16_f32 v15, v16, v17
	global_store_dwordx2 v122, v[14:15], s[20:21] offset:32
	v_mov_b32_e32 v167, v171
	s_nop 1
	v_permlane32_swap_b32_e32 v171, v167
	v_add_f32_e32 v171, v171, v167
	ds_swizzle_b32 v167, v171 offset:0x401f
	s_waitcnt lgkmcnt(0)
	v_add_f32_e32 v171, v171, v167
	v_cmp_gt_u32_e32 vcc, 16, v160
	s_and_saveexec_b64 s[98:99], vcc
	global_store_dword v166, v171, s[14:15] offset:0
	s_or_b64 exec, exec, s[98:99]
	v_mov_b32_e32 v171, 0
	v_lshlrev_b32_e32 v167, 16, v232
	v_and_b32_e32 v168, 0xffff0000, v232
	v_lshlrev_b32_e32 v169, 16, v233
	v_and_b32_e32 v170, 0xffff0000, v233
	v_add_f32_e32 v18, v18, v167
	v_add_f32_e32 v19, v19, v168
	v_add_f32_e32 v20, v20, v169
	v_add_f32_e32 v21, v21, v170
	v_fma_f32 v171, v18, v18, v171
	v_fma_f32 v171, v19, v19, v171
	v_fma_f32 v171, v20, v20, v171
	v_fma_f32 v171, v21, v21, v171
	v_cvt_pk_bf16_f32 v18, v18, v19
	v_cvt_pk_bf16_f32 v19, v20, v21
	global_store_dwordx2 v164, v[18:19], s[20:21] offset:1024
	v_lshlrev_b32_e32 v167, 16, v234
	v_and_b32_e32 v168, 0xffff0000, v234
	v_lshlrev_b32_e32 v169, 16, v235
	v_and_b32_e32 v170, 0xffff0000, v235
	v_add_f32_e32 v22, v22, v167
	v_add_f32_e32 v23, v23, v168
	v_add_f32_e32 v24, v24, v169
	v_add_f32_e32 v25, v25, v170
	v_fma_f32 v171, v22, v22, v171
	v_fma_f32 v171, v23, v23, v171
	v_fma_f32 v171, v24, v24, v171
	v_fma_f32 v171, v25, v25, v171
	v_cvt_pk_bf16_f32 v22, v22, v23
	v_cvt_pk_bf16_f32 v23, v24, v25
	global_store_dwordx2 v164, v[22:23], s[20:21] offset:1056
	v_lshlrev_b32_e32 v167, 16, v236
	v_and_b32_e32 v168, 0xffff0000, v236
	v_lshlrev_b32_e32 v169, 16, v237
	v_and_b32_e32 v170, 0xffff0000, v237
	v_add_f32_e32 v26, v26, v167
	v_add_f32_e32 v27, v27, v168
	v_add_f32_e32 v28, v28, v169
	v_add_f32_e32 v29, v29, v170
	v_fma_f32 v171, v26, v26, v171
	v_fma_f32 v171, v27, v27, v171
	v_fma_f32 v171, v28, v28, v171
	v_fma_f32 v171, v29, v29, v171
	v_cvt_pk_bf16_f32 v26, v26, v27
	v_cvt_pk_bf16_f32 v27, v28, v29
	global_store_dwordx2 v122, v[26:27], s[20:21] offset:1024
	v_lshlrev_b32_e32 v167, 16, v238
	v_and_b32_e32 v168, 0xffff0000, v238
	v_lshlrev_b32_e32 v169, 16, v239
	v_and_b32_e32 v170, 0xffff0000, v239
	v_add_f32_e32 v30, v30, v167
	v_add_f32_e32 v31, v31, v168
	v_add_f32_e32 v32, v32, v169
	v_add_f32_e32 v33, v33, v170
	v_fma_f32 v171, v30, v30, v171
	v_fma_f32 v171, v31, v31, v171
	v_fma_f32 v171, v32, v32, v171
	v_fma_f32 v171, v33, v33, v171
	v_cvt_pk_bf16_f32 v30, v30, v31
	v_cvt_pk_bf16_f32 v31, v32, v33
	global_store_dwordx2 v122, v[30:31], s[20:21] offset:1056
	v_mov_b32_e32 v167, v171
	s_nop 1
	v_permlane32_swap_b32_e32 v171, v167
	v_add_f32_e32 v171, v171, v167
	ds_swizzle_b32 v167, v171 offset:0x401f
	s_waitcnt lgkmcnt(0)
; DI u32x4 pack8(const float (&v)[8]) { u32x4 r = {pk2(v[0], v[1]), pk2(v[2], v[3]), pk2(v[4], v[5]), pk2(v[6], v[7])}; return r; }
; DI void tile_outproj(const Params& p, int l, const Chunk& ck, int tile, int next, PF& pf, char* smem) {
;     ...
;   const int row = tid >> 1, half = tid & 1; float ssq = 0.f;
;   u16* xb = (u16*)(p.ws + OFF_XB) + (size_t)(m0 + row) * 1024 + n0 + half * 64;
; #pragma unroll
;   for (int c8 = 0; c8 < 8; ++c8) {
;     float v[8], x[8]; cs_ld8(Cs, row, half * 64 + c8 * 8, v); unpack8(*(const u32x4*)(xb + c8 * 8), x);
; #pragma unroll
;     for (int j = 0; j < 8; ++j) { v[j] += x[j]; ssq += v[j] * v[j]; }
;     *(u32x4*)(xb + c8 * 8) = pack8(v);
;   }
;   ((float*)(p.ws + OFF_PSMID))[(size_t)(m0 + row) * 16 + ni * 2 + half] = ssq;
	v_add_f32_e32 v171, v171, v167
	v_cmp_gt_u32_e32 vcc, 16, v160
	s_and_saveexec_b64 s[98:99], vcc
	global_store_dword v166, v171, s[14:15] offset:1024
	s_or_b64 exec, exec, s[98:99]
	v_mov_b32_e32 v171, 0
	v_lshlrev_b32_e32 v167, 16, v240
	v_and_b32_e32 v168, 0xffff0000, v240
	v_lshlrev_b32_e32 v169, 16, v241
	v_and_b32_e32 v170, 0xffff0000, v241
	v_add_f32_e32 v34, v34, v167
	v_add_f32_e32 v35, v35, v168
	v_add_f32_e32 v36, v36, v169
	v_add_f32_e32 v37, v37, v170
	v_fma_f32 v171, v34, v34, v171
	v_fma_f32 v171, v35, v35, v171
	v_fma_f32 v171, v36, v36, v171
	v_fma_f32 v171, v37, v37, v171
	v_cvt_pk_bf16_f32 v34, v34, v35
	v_cvt_pk_bf16_f32 v35, v36, v37
	global_store_dwordx2 v164, v[34:35], s[20:21] offset:2048
	v_lshlrev_b32_e32 v167, 16, v242
	v_and_b32_e32 v168, 0xffff0000, v242
	v_lshlrev_b32_e32 v169, 16, v243
	v_and_b32_e32 v170, 0xffff0000, v243
	v_add_f32_e32 v38, v38, v167
	v_add_f32_e32 v39, v39, v168
	v_add_f32_e32 v40, v40, v169
	v_add_f32_e32 v41, v41, v170
	v_fma_f32 v171, v38, v38, v171
	v_fma_f32 v171, v39, v39, v171
	v_fma_f32 v171, v40, v40, v171
	v_fma_f32 v171, v41, v41, v171
	v_cvt_pk_bf16_f32 v38, v38, v39
	v_cvt_pk_bf16_f32 v39, v40, v41
	global_store_dwordx2 v164, v[38:39], s[20:21] offset:2080
	v_lshlrev_b32_e32 v167, 16, v244
	v_and_b32_e32 v168, 0xffff0000, v244
	v_lshlrev_b32_e32 v169, 16, v245
	v_and_b32_e32 v170, 0xffff0000, v245
	v_add_f32_e32 v42, v42, v167
	v_add_f32_e32 v43, v43, v168
	v_add_f32_e32 v44, v44, v169
	v_add_f32_e32 v45, v45, v170
	v_fma_f32 v171, v42, v42, v171
	v_fma_f32 v171, v43, v43, v171
	v_fma_f32 v171, v44, v44, v171
	v_fma_f32 v171, v45, v45, v171
	v_cvt_pk_bf16_f32 v42, v42, v43
	v_cvt_pk_bf16_f32 v43, v44, v45
	global_store_dwordx2 v122, v[42:43], s[20:21] offset:2048
	v_lshlrev_b32_e32 v167, 16, v246
	v_and_b32_e32 v168, 0xffff0000, v246
	v_lshlrev_b32_e32 v169, 16, v247
	v_and_b32_e32 v170, 0xffff0000, v247
	v_add_f32_e32 v46, v46, v167
	v_add_f32_e32 v47, v47, v168
	v_add_f32_e32 v48, v48, v169
	v_add_f32_e32 v49, v49, v170
	v_fma_f32 v171, v46, v46, v171
	v_fma_f32 v171, v47, v47, v171
	v_fma_f32 v171, v48, v48, v171
	v_fma_f32 v171, v49, v49, v171
	v_cvt_pk_bf16_f32 v46, v46, v47
	v_cvt_pk_bf16_f32 v47, v48, v49
	global_store_dwordx2 v122, v[46:47], s[20:21] offset:2080
	v_mov_b32_e32 v167, v171
	s_nop 1
	v_permlane32_swap_b32_e32 v171, v167
	v_add_f32_e32 v171, v171, v167
	ds_swizzle_b32 v167, v171 offset:0x401f
	s_waitcnt lgkmcnt(0)
	v_add_f32_e32 v171, v171, v167
	v_cmp_gt_u32_e32 vcc, 16, v160
	s_and_saveexec_b64 s[98:99], vcc
	global_store_dword v166, v171, s[14:15] offset:2048
	s_or_b64 exec, exec, s[98:99]
	v_mov_b32_e32 v171, 0
	v_lshlrev_b32_e32 v167, 16, v248
	v_and_b32_e32 v168, 0xffff0000, v248
	v_lshlrev_b32_e32 v169, 16, v249
	v_and_b32_e32 v170, 0xffff0000, v249
	v_add_f32_e32 v50, v50, v167
	v_add_f32_e32 v51, v51, v168
	v_add_f32_e32 v52, v52, v169
	v_add_f32_e32 v53, v53, v170
	v_fma_f32 v171, v50, v50, v171
	v_fma_f32 v171, v51, v51, v171
	v_fma_f32 v171, v52, v52, v171
	v_fma_f32 v171, v53, v53, v171
	v_cvt_pk_bf16_f32 v50, v50, v51
	v_cvt_pk_bf16_f32 v51, v52, v53
	global_store_dwordx2 v164, v[50:51], s[20:21] offset:3072
	v_lshlrev_b32_e32 v167, 16, v250
	v_and_b32_e32 v168, 0xffff0000, v250
	v_lshlrev_b32_e32 v169, 16, v251
	v_and_b32_e32 v170, 0xffff0000, v251
	v_add_f32_e32 v54, v54, v167
	v_add_f32_e32 v55, v55, v168
	v_add_f32_e32 v56, v56, v169
	v_add_f32_e32 v57, v57, v170
	v_fma_f32 v171, v54, v54, v171
	v_fma_f32 v171, v55, v55, v171
	v_fma_f32 v171, v56, v56, v171
	v_fma_f32 v171, v57, v57, v171
	v_cvt_pk_bf16_f32 v54, v54, v55
	v_cvt_pk_bf16_f32 v55, v56, v57
	global_store_dwordx2 v164, v[54:55], s[20:21] offset:3104
	v_lshlrev_b32_e32 v167, 16, v156
	v_and_b32_e32 v168, 0xffff0000, v156
	v_lshlrev_b32_e32 v169, 16, v157
	v_and_b32_e32 v170, 0xffff0000, v157
	v_add_f32_e32 v58, v58, v167
	v_add_f32_e32 v59, v59, v168
	v_add_f32_e32 v60, v60, v169
	v_add_f32_e32 v61, v61, v170
	v_fma_f32 v171, v58, v58, v171
	v_fma_f32 v171, v59, v59, v171
	v_fma_f32 v171, v60, v60, v171
	v_fma_f32 v171, v61, v61, v171
	v_cvt_pk_bf16_f32 v58, v58, v59
	v_cvt_pk_bf16_f32 v59, v60, v61
	global_store_dwordx2 v122, v[58:59], s[20:21] offset:3072
	v_lshlrev_b32_e32 v167, 16, v158
	v_and_b32_e32 v168, 0xffff0000, v158
	v_lshlrev_b32_e32 v169, 16, v159
	v_and_b32_e32 v170, 0xffff0000, v159
	v_add_f32_e32 v62, v62, v167
	v_add_f32_e32 v63, v63, v168
	v_add_f32_e32 v64, v64, v169
	v_add_f32_e32 v65, v65, v170
	v_fma_f32 v171, v62, v62, v171
	v_fma_f32 v171, v63, v63, v171
	v_fma_f32 v171, v64, v64, v171
	v_fma_f32 v171, v65, v65, v171
	v_cvt_pk_bf16_f32 v62, v62, v63
	v_cvt_pk_bf16_f32 v63, v64, v65
	global_store_dwordx2 v122, v[62:63], s[20:21] offset:3104
	v_mov_b32_e32 v167, v171
	s_nop 1
	v_permlane32_swap_b32_e32 v171, v167
	v_add_f32_e32 v171, v171, v167
	ds_swizzle_b32 v167, v171 offset:0x401f
	s_waitcnt lgkmcnt(0)
	v_add_f32_e32 v171, v171, v167
	v_cmp_gt_u32_e32 vcc, 16, v160
	s_and_saveexec_b64 s[98:99], vcc
	global_store_dword v166, v171, s[14:15] offset:3072
	s_or_b64 exec, exec, s[98:99]
	v_add_u32_e32 v164, 0x400000, v164
	v_add_u32_e32 v122, 0x400000, v122
	global_load_dwordx2 v[224:225], v164, s[20:21] offset:0
	global_load_dwordx2 v[226:227], v164, s[20:21] offset:32
	global_load_dwordx2 v[228:229], v122, s[20:21] offset:0
	global_load_dwordx2 v[230:231], v122, s[20:21] offset:32
	global_load_dwordx2 v[232:233], v164, s[20:21] offset:1024
	global_load_dwordx2 v[234:235], v164, s[20:21] offset:1056
	global_load_dwordx2 v[236:237], v122, s[20:21] offset:1024
	global_load_dwordx2 v[238:239], v122, s[20:21] offset:1056
	global_load_dwordx2 v[240:241], v164, s[20:21] offset:2048
	global_load_dwordx2 v[242:243], v164, s[20:21] offset:2080
	global_load_dwordx2 v[244:245], v122, s[20:21] offset:2048
	global_load_dwordx2 v[246:247], v122, s[20:21] offset:2080
	global_load_dwordx2 v[248:249], v164, s[20:21] offset:3072
	global_load_dwordx2 v[250:251], v164, s[20:21] offset:3104
	global_load_dwordx2 v[156:157], v122, s[20:21] offset:3072
	global_load_dwordx2 v[158:159], v122, s[20:21] offset:3104
	s_waitcnt vmcnt(0)
; DI u32x4 pack8(const float (&v)[8]) { u32x4 r = {pk2(v[0], v[1]), pk2(v[2], v[3]), pk2(v[4], v[5]), pk2(v[6], v[7])}; return r; }
; DI void tile_outproj(const Params& p, int l, const Chunk& ck, int tile, int next, PF& pf, char* smem) {
;     ...
;   const int row = tid >> 1, half = tid & 1; float ssq = 0.f;
;   u16* xb = (u16*)(p.ws + OFF_XB) + (size_t)(m0 + row) * 1024 + n0 + half * 64;
; #pragma unroll
;   for (int c8 = 0; c8 < 8; ++c8) {
;     float v[8], x[8]; cs_ld8(Cs, row, half * 64 + c8 * 8, v); unpack8(*(const u32x4*)(xb + c8 * 8), x);
; #pragma unroll
;     for (int j = 0; j < 8; ++j) { v[j] += x[j]; ssq += v[j] * v[j]; }
;     *(u32x4*)(xb + c8 * 8) = pack8(v);
;   }
;   ((float*)(p.ws + OFF_PSMID))[(size_t)(m0 + row) * 16 + ni * 2 + half] = ssq;
	v_mov_b32_e32 v171, 0
	v_lshlrev_b32_e32 v167, 16, v224
	v_and_b32_e32 v168, 0xffff0000, v224
	v_lshlrev_b32_e32 v169, 16, v225
	v_and_b32_e32 v170, 0xffff0000, v225
	v_add_f32_e32 v74, v74, v167
	v_add_f32_e32 v75, v75, v168
	v_add_f32_e32 v76, v76, v169
	v_add_f32_e32 v77, v77, v170
	v_fma_f32 v171, v74, v74, v171
	v_fma_f32 v171, v75, v75, v171
	v_fma_f32 v171, v76, v76, v171
	v_fma_f32 v171, v77, v77, v171
	v_cvt_pk_bf16_f32 v74, v74, v75
	v_cvt_pk_bf16_f32 v75, v76, v77
	global_store_dwordx2 v164, v[74:75], s[20:21]
	v_lshlrev_b32_e32 v167, 16, v226
	v_and_b32_e32 v168, 0xffff0000, v226
	v_lshlrev_b32_e32 v169, 16, v227
	v_and_b32_e32 v170, 0xffff0000, v227
	v_add_f32_e32 v78, v78, v167
	v_add_f32_e32 v79, v79, v168
	v_add_f32_e32 v80, v80, v169
	v_add_f32_e32 v81, v81, v170
	v_fma_f32 v171, v78, v78, v171
	v_fma_f32 v171, v79, v79, v171
	v_fma_f32 v171, v80, v80, v171
	v_fma_f32 v171, v81, v81, v171
	v_cvt_pk_bf16_f32 v78, v78, v79
	v_cvt_pk_bf16_f32 v79, v80, v81
	global_store_dwordx2 v164, v[78:79], s[20:21] offset:32
	v_lshlrev_b32_e32 v167, 16, v228
	v_and_b32_e32 v168, 0xffff0000, v228
	v_lshlrev_b32_e32 v169, 16, v229
	v_and_b32_e32 v170, 0xffff0000, v229
	v_add_f32_e32 v82, v82, v167
	v_add_f32_e32 v83, v83, v168
	v_add_f32_e32 v84, v84, v169
	v_add_f32_e32 v85, v85, v170
	v_fma_f32 v171, v82, v82, v171
	v_fma_f32 v171, v83, v83, v171
	v_fma_f32 v171, v84, v84, v171
	v_fma_f32 v171, v85, v85, v171
	v_cvt_pk_bf16_f32 v82, v82, v83
	v_cvt_pk_bf16_f32 v83, v84, v85
	global_store_dwordx2 v122, v[82:83], s[20:21]
	v_lshlrev_b32_e32 v167, 16, v230
	v_and_b32_e32 v168, 0xffff0000, v230
	v_lshlrev_b32_e32 v169, 16, v231
	v_and_b32_e32 v170, 0xffff0000, v231
	v_add_f32_e32 v86, v86, v167
	v_add_f32_e32 v87, v87, v168
	v_add_f32_e32 v88, v88, v169
	v_add_f32_e32 v89, v89, v170
	v_fma_f32 v171, v86, v86, v171
	v_fma_f32 v171, v87, v87, v171
	v_fma_f32 v171, v88, v88, v171
	v_fma_f32 v171, v89, v89, v171
	v_cvt_pk_bf16_f32 v86, v86, v87
	v_cvt_pk_bf16_f32 v87, v88, v89
	global_store_dwordx2 v122, v[86:87], s[20:21] offset:32
	v_mov_b32_e32 v167, v171
	s_nop 1
	v_permlane32_swap_b32_e32 v171, v167
	v_add_f32_e32 v171, v171, v167
	ds_swizzle_b32 v167, v171 offset:0x401f
	s_waitcnt lgkmcnt(0)
	v_add_f32_e32 v171, v171, v167
	v_cmp_gt_u32_e32 vcc, 16, v160
	s_and_saveexec_b64 s[98:99], vcc
	global_store_dword v166, v171, s[14:15] offset:8
	s_or_b64 exec, exec, s[98:99]
	v_mov_b32_e32 v171, 0
	v_lshlrev_b32_e32 v167, 16, v232
	v_and_b32_e32 v168, 0xffff0000, v232
	v_lshlrev_b32_e32 v169, 16, v233
	v_and_b32_e32 v170, 0xffff0000, v233
	v_add_f32_e32 v90, v90, v167
	v_add_f32_e32 v91, v91, v168
	v_add_f32_e32 v92, v92, v169
	v_add_f32_e32 v93, v93, v170
	v_fma_f32 v171, v90, v90, v171
	v_fma_f32 v171, v91, v91, v171
	v_fma_f32 v171, v92, v92, v171
	v_fma_f32 v171, v93, v93, v171
	v_cvt_pk_bf16_f32 v90, v90, v91
	v_cvt_pk_bf16_f32 v91, v92, v93
	global_store_dwordx2 v164, v[90:91], s[20:21] offset:1024
	v_lshlrev_b32_e32 v167, 16, v234
	v_and_b32_e32 v168, 0xffff0000, v234
	v_lshlrev_b32_e32 v169, 16, v235
	v_and_b32_e32 v170, 0xffff0000, v235
	v_add_f32_e32 v94, v94, v167
	v_add_f32_e32 v95, v95, v168
	v_add_f32_e32 v96, v96, v169
	v_add_f32_e32 v97, v97, v170
	v_fma_f32 v171, v94, v94, v171
	v_fma_f32 v171, v95, v95, v171
	v_fma_f32 v171, v96, v96, v171
	v_fma_f32 v171, v97, v97, v171
	v_cvt_pk_bf16_f32 v94, v94, v95
	v_cvt_pk_bf16_f32 v95, v96, v97
	global_store_dwordx2 v164, v[94:95], s[20:21] offset:1056
	v_lshlrev_b32_e32 v167, 16, v236
	v_and_b32_e32 v168, 0xffff0000, v236
	v_lshlrev_b32_e32 v169, 16, v237
	v_and_b32_e32 v170, 0xffff0000, v237
	v_add_f32_e32 v98, v98, v167
	v_add_f32_e32 v99, v99, v168
	v_add_f32_e32 v100, v100, v169
	v_add_f32_e32 v101, v101, v170
	v_fma_f32 v171, v98, v98, v171
	v_fma_f32 v171, v99, v99, v171
	v_fma_f32 v171, v100, v100, v171
	v_fma_f32 v171, v101, v101, v171
	v_cvt_pk_bf16_f32 v98, v98, v99
	v_cvt_pk_bf16_f32 v99, v100, v101
	global_store_dwordx2 v122, v[98:99], s[20:21] offset:1024
	v_lshlrev_b32_e32 v167, 16, v238
	v_and_b32_e32 v168, 0xffff0000, v238
	v_lshlrev_b32_e32 v169, 16, v239
	v_and_b32_e32 v170, 0xffff0000, v239
	v_add_f32_e32 v102, v102, v167
	v_add_f32_e32 v103, v103, v168
	v_add_f32_e32 v104, v104, v169
	v_add_f32_e32 v105, v105, v170
	v_fma_f32 v171, v102, v102, v171
	v_fma_f32 v171, v103, v103, v171
	v_fma_f32 v171, v104, v104, v171
	v_fma_f32 v171, v105, v105, v171
	v_cvt_pk_bf16_f32 v102, v102, v103
	v_cvt_pk_bf16_f32 v103, v104, v105
	global_store_dwordx2 v122, v[102:103], s[20:21] offset:1056
	v_mov_b32_e32 v167, v171
	s_nop 1
	v_permlane32_swap_b32_e32 v171, v167
	v_add_f32_e32 v171, v171, v167
	ds_swizzle_b32 v167, v171 offset:0x401f
	s_waitcnt lgkmcnt(0)
; DI u32x4 pack8(const float (&v)[8]) { u32x4 r = {pk2(v[0], v[1]), pk2(v[2], v[3]), pk2(v[4], v[5]), pk2(v[6], v[7])}; return r; }
; DI void tile_outproj(const Params& p, int l, const Chunk& ck, int tile, int next, PF& pf, char* smem) {
;     ...
;   const int row = tid >> 1, half = tid & 1; float ssq = 0.f;
;   u16* xb = (u16*)(p.ws + OFF_XB) + (size_t)(m0 + row) * 1024 + n0 + half * 64;
; #pragma unroll
;   for (int c8 = 0; c8 < 8; ++c8) {
;     float v[8], x[8]; cs_ld8(Cs, row, half * 64 + c8 * 8, v); unpack8(*(const u32x4*)(xb + c8 * 8), x);
; #pragma unroll
;     for (int j = 0; j < 8; ++j) { v[j] += x[j]; ssq += v[j] * v[j]; }
;     *(u32x4*)(xb + c8 * 8) = pack8(v);
;   }
;   ((float*)(p.ws + OFF_PSMID))[(size_t)(m0 + row) * 16 + ni * 2 + half] = ssq;
	v_add_f32_e32 v171, v171, v167
	v_cmp_gt_u32_e32 vcc, 16, v160
	s_and_saveexec_b64 s[98:99], vcc
	global_store_dword v166, v171, s[14:15] offset:1032
	s_or_b64 exec, exec, s[98:99]
	v_mov_b32_e32 v171, 0
	v_lshlrev_b32_e32 v167, 16, v240
	v_and_b32_e32 v168, 0xffff0000, v240
	v_lshlrev_b32_e32 v169, 16, v241
	v_and_b32_e32 v170, 0xffff0000, v241
	v_add_f32_e32 v106, v106, v167
	v_add_f32_e32 v107, v107, v168
	v_add_f32_e32 v108, v108, v169
	v_add_f32_e32 v109, v109, v170
	v_fma_f32 v171, v106, v106, v171
	v_fma_f32 v171, v107, v107, v171
	v_fma_f32 v171, v108, v108, v171
	v_fma_f32 v171, v109, v109, v171
	v_cvt_pk_bf16_f32 v106, v106, v107
	v_cvt_pk_bf16_f32 v107, v108, v109
	global_store_dwordx2 v164, v[106:107], s[20:21] offset:2048
	v_lshlrev_b32_e32 v167, 16, v242
	v_and_b32_e32 v168, 0xffff0000, v242
	v_lshlrev_b32_e32 v169, 16, v243
	v_and_b32_e32 v170, 0xffff0000, v243
	v_add_f32_e32 v110, v110, v167
	v_add_f32_e32 v111, v111, v168
	v_add_f32_e32 v112, v112, v169
	v_add_f32_e32 v113, v113, v170
	v_fma_f32 v171, v110, v110, v171
	v_fma_f32 v171, v111, v111, v171
	v_fma_f32 v171, v112, v112, v171
	v_fma_f32 v171, v113, v113, v171
	v_cvt_pk_bf16_f32 v110, v110, v111
	v_cvt_pk_bf16_f32 v111, v112, v113
	global_store_dwordx2 v164, v[110:111], s[20:21] offset:2080
	v_lshlrev_b32_e32 v167, 16, v244
	v_and_b32_e32 v168, 0xffff0000, v244
	v_lshlrev_b32_e32 v169, 16, v245
	v_and_b32_e32 v170, 0xffff0000, v245
	v_add_f32_e32 v114, v114, v167
	v_add_f32_e32 v115, v115, v168
	v_add_f32_e32 v116, v116, v169
	v_add_f32_e32 v117, v117, v170
	v_fma_f32 v171, v114, v114, v171
	v_fma_f32 v171, v115, v115, v171
	v_fma_f32 v171, v116, v116, v171
	v_fma_f32 v171, v117, v117, v171
	v_cvt_pk_bf16_f32 v114, v114, v115
	v_cvt_pk_bf16_f32 v115, v116, v117
	global_store_dwordx2 v122, v[114:115], s[20:21] offset:2048
	v_lshlrev_b32_e32 v167, 16, v246
	v_and_b32_e32 v168, 0xffff0000, v246
	v_lshlrev_b32_e32 v169, 16, v247
	v_and_b32_e32 v170, 0xffff0000, v247
	v_add_f32_e32 v118, v118, v167
	v_add_f32_e32 v119, v119, v168
	v_add_f32_e32 v120, v120, v169
	v_add_f32_e32 v121, v121, v170
	v_fma_f32 v171, v118, v118, v171
	v_fma_f32 v171, v119, v119, v171
	v_fma_f32 v171, v120, v120, v171
	v_fma_f32 v171, v121, v121, v171
	v_cvt_pk_bf16_f32 v118, v118, v119
	v_cvt_pk_bf16_f32 v119, v120, v121
	global_store_dwordx2 v122, v[118:119], s[20:21] offset:2080
	v_mov_b32_e32 v167, v171
	s_nop 1
	v_permlane32_swap_b32_e32 v171, v167
	v_add_f32_e32 v171, v171, v167
	ds_swizzle_b32 v167, v171 offset:0x401f
	s_waitcnt lgkmcnt(0)
	v_add_f32_e32 v171, v171, v167
	v_cmp_gt_u32_e32 vcc, 16, v160
	s_and_saveexec_b64 s[98:99], vcc
	global_store_dword v166, v171, s[14:15] offset:2056
	s_or_b64 exec, exec, s[98:99]
	v_mov_b32_e32 v171, 0
	v_lshlrev_b32_e32 v167, 16, v248
	v_and_b32_e32 v168, 0xffff0000, v248
	v_lshlrev_b32_e32 v169, 16, v249
	v_and_b32_e32 v170, 0xffff0000, v249
	v_add_f32_e32 v208, v208, v167
	v_add_f32_e32 v209, v209, v168
	v_add_f32_e32 v210, v210, v169
	v_add_f32_e32 v211, v211, v170
	v_fma_f32 v171, v208, v208, v171
	v_fma_f32 v171, v209, v209, v171
	v_fma_f32 v171, v210, v210, v171
	v_fma_f32 v171, v211, v211, v171
	v_cvt_pk_bf16_f32 v208, v208, v209
	v_cvt_pk_bf16_f32 v209, v210, v211
	global_store_dwordx2 v164, v[208:209], s[20:21] offset:3072
	v_lshlrev_b32_e32 v167, 16, v250
	v_and_b32_e32 v168, 0xffff0000, v250
	v_lshlrev_b32_e32 v169, 16, v251
	v_and_b32_e32 v170, 0xffff0000, v251
	v_add_f32_e32 v212, v212, v167
	v_add_f32_e32 v213, v213, v168
	v_add_f32_e32 v214, v214, v169
	v_add_f32_e32 v215, v215, v170
	v_fma_f32 v171, v212, v212, v171
	v_fma_f32 v171, v213, v213, v171
	v_fma_f32 v171, v214, v214, v171
	v_fma_f32 v171, v215, v215, v171
	v_cvt_pk_bf16_f32 v212, v212, v213
	v_cvt_pk_bf16_f32 v213, v214, v215
	global_store_dwordx2 v164, v[212:213], s[20:21] offset:3104
	v_lshlrev_b32_e32 v167, 16, v156
	v_and_b32_e32 v168, 0xffff0000, v156
	v_lshlrev_b32_e32 v169, 16, v157
	v_and_b32_e32 v170, 0xffff0000, v157
	v_add_f32_e32 v216, v216, v167
	v_add_f32_e32 v217, v217, v168
	v_add_f32_e32 v218, v218, v169
	v_add_f32_e32 v219, v219, v170
	v_fma_f32 v171, v216, v216, v171
	v_fma_f32 v171, v217, v217, v171
	v_fma_f32 v171, v218, v218, v171
	v_fma_f32 v171, v219, v219, v171
	v_cvt_pk_bf16_f32 v216, v216, v217
	v_cvt_pk_bf16_f32 v217, v218, v219
	global_store_dwordx2 v122, v[216:217], s[20:21] offset:3072
	v_lshlrev_b32_e32 v167, 16, v158
	v_and_b32_e32 v168, 0xffff0000, v158
	v_lshlrev_b32_e32 v169, 16, v159
	v_and_b32_e32 v170, 0xffff0000, v159
	v_add_f32_e32 v220, v220, v167
	v_add_f32_e32 v221, v221, v168
	v_add_f32_e32 v222, v222, v169
	v_add_f32_e32 v223, v223, v170
	v_fma_f32 v171, v220, v220, v171
	v_fma_f32 v171, v221, v221, v171
	v_fma_f32 v171, v222, v222, v171
	v_fma_f32 v171, v223, v223, v171
	v_cvt_pk_bf16_f32 v220, v220, v221
	v_cvt_pk_bf16_f32 v221, v222, v223
	global_store_dwordx2 v122, v[220:221], s[20:21] offset:3104
	v_mov_b32_e32 v167, v171
	s_nop 1
	v_permlane32_swap_b32_e32 v171, v167
	v_add_f32_e32 v171, v171, v167
	ds_swizzle_b32 v167, v171 offset:0x401f
	s_waitcnt lgkmcnt(0)
	v_add_f32_e32 v171, v171, v167
	v_cmp_gt_u32_e32 vcc, 16, v160
	s_and_saveexec_b64 s[98:99], vcc
	global_store_dword v166, v171, s[14:15] offset:3080
	s_or_b64 exec, exec, s[98:99]
	s_branch .LBB1_254

; #define BLOAD(A_, B_, kt) do { _Pragma("unroll") for (int i = 0; i < 4; ++i) { \
;     A_[i] = *(const u32x4*)((const char*)Ap + (aoff + (unsigned)(32 * i * lda + (kt) * 64) * 2u)); B_[i] = *(const u32x4*)((const char*)Wt + (woff + (unsigned)(32 * i * K + (kt) * 64) * 2u)); } } while (0)
; #define BLOAD(A_, B_, kt) do { _Pragma("unroll") for (int i = 0; i < 4; ++i) { \
;     A_[i] = *(const u32x4*)((const char*)Ap + (aoff + (unsigned)(32 * i * lda + (kt) * 64) * 2u)); B_[i] = *(const u32x4*)((const char*)Wt + (woff + (unsigned)(32 * i * K + (kt) * 64) * 2u)); } } while (0)
; #define BSTORE(A_, B_, buf) do { _Pragma("unroll") for (int i = 0; i < 4; ++i) { \
;     *(u32x4*)&As[(buf) * GBUF + (srow + 32 * i) * LDT + sc8] = A_[i]; \
;     *(u32x4*)&Bs[(buf) * GBUF + (srow + 32 * i) * LDT + sc8] = B_[i]; } } while (0)
; template <int NK>
; DI void gemm_run(PF& pf, const u16* __restrict__ Ap, int lda, const u16* __restrict__ Wt, f32x16 (&acc)[2][2], char* smem) {
;     ...
; #pragma unroll
;   for (int kt = 0; kt < nk; kt += 2) {
;     BCOMP(0);
;     BSTORE(pf.a1, pf.b1, 1);
;     if (kt + 3 < nk) BLOAD(pf.a1, pf.b1, kt + 3);
;     __syncthreads();
;     BCOMP(1);
;     if (kt + 2 < nk) { BSTORE(pf.a0, pf.b0, 0); if (kt + 4 < nk) BLOAD(pf.a0, pf.b0, kt + 4); }
;     __syncthreads();
;   }
.Linp_kloop:
	s_waitcnt vmcnt(6)
	s_barrier
	ds_read_b128 v[224:227], v126 offset:0
	ds_read_b128 v[240:243], v128 offset:0
	ds_read_b128 v[244:247], v128 offset:1024
	ds_read_b128 v[248:251], v128 offset:2048
	ds_read_b128 v[156:159], v128 offset:3072
	ds_read_b128 v[228:231], v126 offset:1024
	ds_read_b128 v[232:235], v126 offset:2048
	ds_read_b128 v[236:239], v126 offset:3072
	ds_read_b128 v[160:163], v128 offset:8192
	ds_read_b128 v[164:167], v128 offset:9216
	ds_read_b128 v[168:171], v128 offset:10240
	ds_read_b128 v[122:125], v128 offset:11264
	s_waitcnt lgkmcnt(10)
	v_mfma_f32_16x16x32_bf16 v[2:5], v[224:227], v[240:243], v[2:5]
	s_waitcnt lgkmcnt(9)
	v_mfma_f32_16x16x32_bf16 v[6:9], v[224:227], v[244:247], v[6:9]
	s_waitcnt lgkmcnt(8)
	v_mfma_f32_16x16x32_bf16 v[10:13], v[224:227], v[248:251], v[10:13]
	s_waitcnt lgkmcnt(7)
	v_mfma_f32_16x16x32_bf16 v[14:17], v[224:227], v[156:159], v[14:17]
	s_waitcnt lgkmcnt(6)
	v_mfma_f32_16x16x32_bf16 v[18:21], v[228:231], v[240:243], v[18:21]
	v_mfma_f32_16x16x32_bf16 v[22:25], v[228:231], v[244:247], v[22:25]
	v_mfma_f32_16x16x32_bf16 v[26:29], v[228:231], v[248:251], v[26:29]
	v_mfma_f32_16x16x32_bf16 v[30:33], v[228:231], v[156:159], v[30:33]
	s_waitcnt lgkmcnt(5)
	v_mfma_f32_16x16x32_bf16 v[34:37], v[232:235], v[240:243], v[34:37]
	v_mfma_f32_16x16x32_bf16 v[38:41], v[232:235], v[244:247], v[38:41]
	v_mfma_f32_16x16x32_bf16 v[42:45], v[232:235], v[248:251], v[42:45]
	v_mfma_f32_16x16x32_bf16 v[46:49], v[232:235], v[156:159], v[46:49]
	s_waitcnt lgkmcnt(4)
	v_mfma_f32_16x16x32_bf16 v[50:53], v[236:239], v[240:243], v[50:53]
	v_mfma_f32_16x16x32_bf16 v[54:57], v[236:239], v[244:247], v[54:57]
	v_mfma_f32_16x16x32_bf16 v[58:61], v[236:239], v[248:251], v[58:61]
	v_mfma_f32_16x16x32_bf16 v[62:65], v[236:239], v[156:159], v[62:65]
	s_add_u32 m0, s46, 0xc000
	s_add_u32 s48, s48, 0x100000
	s_addc_u32 s49, s49, 0
	global_load_lds_dwordx4 v138, s[48:49]
	global_load_lds_dwordx4 v139, s[48:49] offset:1024
	s_add_u32 m0, s47, 0xc000
	s_add_u32 s50, s50, s13
	s_addc_u32 s51, s51, 0
	global_load_lds_dwordx4 v140, s[50:51]
	global_load_lds_dwordx4 v141, s[50:51] offset:1024
	global_load_lds_dwordx4 v142, s[50:51] offset:2048
	global_load_lds_dwordx4 v143, s[50:51] offset:3072
	s_waitcnt lgkmcnt(3)
	v_mfma_f32_16x16x32_bf16 v[74:77], v[224:227], v[160:163], v[74:77]
	s_waitcnt lgkmcnt(2)
	v_mfma_f32_16x16x32_bf16 v[78:81], v[224:227], v[164:167], v[78:81]
	s_waitcnt lgkmcnt(1)
	v_mfma_f32_16x16x32_bf16 v[82:85], v[224:227], v[168:171], v[82:85]
	s_waitcnt lgkmcnt(0)
	v_mfma_f32_16x16x32_bf16 v[86:89], v[224:227], v[122:125], v[86:89]
	v_mfma_f32_16x16x32_bf16 v[90:93], v[228:231], v[160:163], v[90:93]
	v_mfma_f32_16x16x32_bf16 v[94:97], v[228:231], v[164:167], v[94:97]
	v_mfma_f32_16x16x32_bf16 v[98:101], v[228:231], v[168:171], v[98:101]
	v_mfma_f32_16x16x32_bf16 v[102:105], v[228:231], v[122:125], v[102:105]
	v_mfma_f32_16x16x32_bf16 v[106:109], v[232:235], v[160:163], v[106:109]
	v_mfma_f32_16x16x32_bf16 v[110:113], v[232:235], v[164:167], v[110:113]
	v_mfma_f32_16x16x32_bf16 v[114:117], v[232:235], v[168:171], v[114:117]
	v_mfma_f32_16x16x32_bf16 v[118:121], v[232:235], v[122:125], v[118:121]
	v_mfma_f32_16x16x32_bf16 v[208:211], v[236:239], v[160:163], v[208:211]
	v_mfma_f32_16x16x32_bf16 v[212:215], v[236:239], v[164:167], v[212:215]
	v_mfma_f32_16x16x32_bf16 v[216:219], v[236:239], v[168:171], v[216:219]
	v_mfma_f32_16x16x32_bf16 v[220:223], v[236:239], v[122:125], v[220:223]
	s_waitcnt vmcnt(6)
	s_barrier
	ds_read_b128 v[224:227], v126 offset:24576
	ds_read_b128 v[240:243], v128 offset:24576
	ds_read_b128 v[244:247], v128 offset:25600
	ds_read_b128 v[248:251], v128 offset:26624
	ds_read_b128 v[156:159], v128 offset:27648
	ds_read_b128 v[228:231], v126 offset:25600
	ds_read_b128 v[232:235], v126 offset:26624
	ds_read_b128 v[236:239], v126 offset:27648
	ds_read_b128 v[160:163], v128 offset:32768
	ds_read_b128 v[164:167], v128 offset:33792
	ds_read_b128 v[168:171], v128 offset:34816
	ds_read_b128 v[122:125], v128 offset:35840
	s_waitcnt lgkmcnt(10)
	v_mfma_f32_16x16x32_bf16 v[2:5], v[224:227], v[240:243], v[2:5]
	s_waitcnt lgkmcnt(9)
	v_mfma_f32_16x16x32_bf16 v[6:9], v[224:227], v[244:247], v[6:9]
	s_waitcnt lgkmcnt(8)
	v_mfma_f32_16x16x32_bf16 v[10:13], v[224:227], v[248:251], v[10:13]
	s_waitcnt lgkmcnt(7)
	v_mfma_f32_16x16x32_bf16 v[14:17], v[224:227], v[156:159], v[14:17]
	s_waitcnt lgkmcnt(6)
	v_mfma_f32_16x16x32_bf16 v[18:21], v[228:231], v[240:243], v[18:21]
	v_mfma_f32_16x16x32_bf16 v[22:25], v[228:231], v[244:247], v[22:25]
	v_mfma_f32_16x16x32_bf16 v[26:29], v[228:231], v[248:251], v[26:29]
	v_mfma_f32_16x16x32_bf16 v[30:33], v[228:231], v[156:159], v[30:33]
	s_waitcnt lgkmcnt(5)
	v_mfma_f32_16x16x32_bf16 v[34:37], v[232:235], v[240:243], v[34:37]
	v_mfma_f32_16x16x32_bf16 v[38:41], v[232:235], v[244:247], v[38:41]
	v_mfma_f32_16x16x32_bf16 v[42:45], v[232:235], v[248:251], v[42:45]
	v_mfma_f32_16x16x32_bf16 v[46:49], v[232:235], v[156:159], v[46:49]
	s_waitcnt lgkmcnt(4)
	v_mfma_f32_16x16x32_bf16 v[50:53], v[236:239], v[240:243], v[50:53]
	v_mfma_f32_16x16x32_bf16 v[54:57], v[236:239], v[244:247], v[54:57]
	v_mfma_f32_16x16x32_bf16 v[58:61], v[236:239], v[248:251], v[58:61]
	v_mfma_f32_16x16x32_bf16 v[62:65], v[236:239], v[156:159], v[62:65]
	s_add_u32 m0, s46, 0x0
	s_add_u32 s48, s48, 0x100000
	s_addc_u32 s49, s49, 0
	global_load_lds_dwordx4 v138, s[48:49]
	global_load_lds_dwordx4 v139, s[48:49] offset:1024
	s_add_u32 m0, s47, 0x0
	s_add_u32 s50, s50, s13
	s_addc_u32 s51, s51, 0
	global_load_lds_dwordx4 v140, s[50:51]
	global_load_lds_dwordx4 v141, s[50:51] offset:1024
	global_load_lds_dwordx4 v142, s[50:51] offset:2048
	global_load_lds_dwordx4 v143, s[50:51] offset:3072
	s_waitcnt lgkmcnt(3)
	v_mfma_f32_16x16x32_bf16 v[74:77], v[224:227], v[160:163], v[74:77]
	s_waitcnt lgkmcnt(2)
	v_mfma_f32_16x16x32_bf16 v[78:81], v[224:227], v[164:167], v[78:81]
	s_waitcnt lgkmcnt(1)
	v_mfma_f32_16x16x32_bf16 v[82:85], v[224:227], v[168:171], v[82:85]
	s_waitcnt lgkmcnt(0)
	v_mfma_f32_16x16x32_bf16 v[86:89], v[224:227], v[122:125], v[86:89]
	v_mfma_f32_16x16x32_bf16 v[90:93], v[228:231], v[160:163], v[90:93]
	v_mfma_f32_16x16x32_bf16 v[94:97], v[228:231], v[164:167], v[94:97]
	v_mfma_f32_16x16x32_bf16 v[98:101], v[228:231], v[168:171], v[98:101]
	v_mfma_f32_16x16x32_bf16 v[102:105], v[228:231], v[122:125], v[102:105]
	v_mfma_f32_16x16x32_bf16 v[106:109], v[232:235], v[160:163], v[106:109]
	v_mfma_f32_16x16x32_bf16 v[110:113], v[232:235], v[164:167], v[110:113]
	v_mfma_f32_16x16x32_bf16 v[114:117], v[232:235], v[168:171], v[114:117]
	v_mfma_f32_16x16x32_bf16 v[118:121], v[232:235], v[122:125], v[118:121]
	v_mfma_f32_16x16x32_bf16 v[208:211], v[236:239], v[160:163], v[208:211]
	v_mfma_f32_16x16x32_bf16 v[212:215], v[236:239], v[164:167], v[212:215]
	v_mfma_f32_16x16x32_bf16 v[216:219], v[236:239], v[168:171], v[216:219]
	v_mfma_f32_16x16x32_bf16 v[220:223], v[236:239], v[122:125], v[220:223]
	s_waitcnt vmcnt(6)
	s_barrier
; #define BLOAD(A_, B_, kt) do { _Pragma("unroll") for (int i = 0; i < 4; ++i) { \
;     A_[i] = *(const u32x4*)((const char*)Ap + (aoff + (unsigned)(32 * i * lda + (kt) * 64) * 2u)); B_[i] = *(const u32x4*)((const char*)Wt + (woff + (unsigned)(32 * i * K + (kt) * 64) * 2u)); } } while (0)
; #define BLOAD(A_, B_, kt) do { _Pragma("unroll") for (int i = 0; i < 4; ++i) { \
;     A_[i] = *(const u32x4*)((const char*)Ap + (aoff + (unsigned)(32 * i * lda + (kt) * 64) * 2u)); B_[i] = *(const u32x4*)((const char*)Wt + (woff + (unsigned)(32 * i * K + (kt) * 64) * 2u)); } } while (0)
; #define BSTORE(A_, B_, buf) do { _Pragma("unroll") for (int i = 0; i < 4; ++i) { \
;     *(u32x4*)&As[(buf) * GBUF + (srow + 32 * i) * LDT + sc8] = A_[i]; \
;     *(u32x4*)&Bs[(buf) * GBUF + (srow + 32 * i) * LDT + sc8] = B_[i]; } } while (0)
; template <int NK>
; DI void gemm_run(PF& pf, const u16* __restrict__ Ap, int lda, const u16* __restrict__ Wt, f32x16 (&acc)[2][2], char* smem) {
;     ...
; #pragma unroll
;   for (int kt = 0; kt < nk; kt += 2) {
;     BCOMP(0);
;     BSTORE(pf.a1, pf.b1, 1);
;     if (kt + 3 < nk) BLOAD(pf.a1, pf.b1, kt + 3);
;     __syncthreads();
;     BCOMP(1);
;     if (kt + 2 < nk) { BSTORE(pf.a0, pf.b0, 0); if (kt + 4 < nk) BLOAD(pf.a0, pf.b0, kt + 4); }
;     __syncthreads();
;   }
	ds_read_b128 v[224:227], v126 offset:49152
	ds_read_b128 v[240:243], v128 offset:49152
	ds_read_b128 v[244:247], v128 offset:50176
	ds_read_b128 v[248:251], v128 offset:51200
	ds_read_b128 v[156:159], v128 offset:52224
	ds_read_b128 v[228:231], v126 offset:50176
	ds_read_b128 v[232:235], v126 offset:51200
	ds_read_b128 v[236:239], v126 offset:52224
	ds_read_b128 v[160:163], v128 offset:57344
	ds_read_b128 v[164:167], v128 offset:58368
	ds_read_b128 v[168:171], v128 offset:59392
	ds_read_b128 v[122:125], v128 offset:60416
	s_waitcnt lgkmcnt(10)
	v_mfma_f32_16x16x32_bf16 v[2:5], v[224:227], v[240:243], v[2:5]
	s_waitcnt lgkmcnt(9)
	v_mfma_f32_16x16x32_bf16 v[6:9], v[224:227], v[244:247], v[6:9]
	s_waitcnt lgkmcnt(8)
	v_mfma_f32_16x16x32_bf16 v[10:13], v[224:227], v[248:251], v[10:13]
	s_waitcnt lgkmcnt(7)
	v_mfma_f32_16x16x32_bf16 v[14:17], v[224:227], v[156:159], v[14:17]
	s_waitcnt lgkmcnt(6)
	v_mfma_f32_16x16x32_bf16 v[18:21], v[228:231], v[240:243], v[18:21]
	v_mfma_f32_16x16x32_bf16 v[22:25], v[228:231], v[244:247], v[22:25]
	v_mfma_f32_16x16x32_bf16 v[26:29], v[228:231], v[248:251], v[26:29]
	v_mfma_f32_16x16x32_bf16 v[30:33], v[228:231], v[156:159], v[30:33]
	s_waitcnt lgkmcnt(5)
	v_mfma_f32_16x16x32_bf16 v[34:37], v[232:235], v[240:243], v[34:37]
	v_mfma_f32_16x16x32_bf16 v[38:41], v[232:235], v[244:247], v[38:41]
	v_mfma_f32_16x16x32_bf16 v[42:45], v[232:235], v[248:251], v[42:45]
	v_mfma_f32_16x16x32_bf16 v[46:49], v[232:235], v[156:159], v[46:49]
	s_waitcnt lgkmcnt(4)
	v_mfma_f32_16x16x32_bf16 v[50:53], v[236:239], v[240:243], v[50:53]
	v_mfma_f32_16x16x32_bf16 v[54:57], v[236:239], v[244:247], v[54:57]
	v_mfma_f32_16x16x32_bf16 v[58:61], v[236:239], v[248:251], v[58:61]
	v_mfma_f32_16x16x32_bf16 v[62:65], v[236:239], v[156:159], v[62:65]
	s_add_u32 m0, s46, 0x6000
	s_add_u32 s48, s48, 0x100000
	s_addc_u32 s49, s49, 0
	global_load_lds_dwordx4 v138, s[48:49]
	global_load_lds_dwordx4 v139, s[48:49] offset:1024
	s_add_u32 m0, s47, 0x6000
	s_add_u32 s50, s50, s13
	s_addc_u32 s51, s51, 0
	global_load_lds_dwordx4 v140, s[50:51]
	global_load_lds_dwordx4 v141, s[50:51] offset:1024
	global_load_lds_dwordx4 v142, s[50:51] offset:2048
	global_load_lds_dwordx4 v143, s[50:51] offset:3072
	s_waitcnt lgkmcnt(3)
	v_mfma_f32_16x16x32_bf16 v[74:77], v[224:227], v[160:163], v[74:77]
	s_waitcnt lgkmcnt(2)
	v_mfma_f32_16x16x32_bf16 v[78:81], v[224:227], v[164:167], v[78:81]
	s_waitcnt lgkmcnt(1)
	v_mfma_f32_16x16x32_bf16 v[82:85], v[224:227], v[168:171], v[82:85]
	s_waitcnt lgkmcnt(0)
	v_mfma_f32_16x16x32_bf16 v[86:89], v[224:227], v[122:125], v[86:89]
	v_mfma_f32_16x16x32_bf16 v[90:93], v[228:231], v[160:163], v[90:93]
	v_mfma_f32_16x16x32_bf16 v[94:97], v[228:231], v[164:167], v[94:97]
	v_mfma_f32_16x16x32_bf16 v[98:101], v[228:231], v[168:171], v[98:101]
	v_mfma_f32_16x16x32_bf16 v[102:105], v[228:231], v[122:125], v[102:105]
	v_mfma_f32_16x16x32_bf16 v[106:109], v[232:235], v[160:163], v[106:109]
	v_mfma_f32_16x16x32_bf16 v[110:113], v[232:235], v[164:167], v[110:113]
	v_mfma_f32_16x16x32_bf16 v[114:117], v[232:235], v[168:171], v[114:117]
	v_mfma_f32_16x16x32_bf16 v[118:121], v[232:235], v[122:125], v[118:121]
	v_mfma_f32_16x16x32_bf16 v[208:211], v[236:239], v[160:163], v[208:211]
	v_mfma_f32_16x16x32_bf16 v[212:215], v[236:239], v[164:167], v[212:215]
	v_mfma_f32_16x16x32_bf16 v[216:219], v[236:239], v[168:171], v[216:219]
	v_mfma_f32_16x16x32_bf16 v[220:223], v[236:239], v[122:125], v[220:223]
	s_sub_u32 s12, s12, 1
	s_cmp_lg_u32 s12, 0
	s_cbranch_scc1 .Linp_kloop
	s_waitcnt vmcnt(6)
	s_barrier
; #define BLOAD(A_, B_, kt) do { _Pragma("unroll") for (int i = 0; i < 4; ++i) { \
;     A_[i] = *(const u32x4*)((const char*)Ap + (aoff + (unsigned)(32 * i * lda + (kt) * 64) * 2u)); B_[i] = *(const u32x4*)((const char*)Wt + (woff + (unsigned)(32 * i * K + (kt) * 64) * 2u)); } } while (0)
; #define BLOAD(A_, B_, kt) do { _Pragma("unroll") for (int i = 0; i < 4; ++i) { \
;     A_[i] = *(const u32x4*)((const char*)Ap + (aoff + (unsigned)(32 * i * lda + (kt) * 64) * 2u)); B_[i] = *(const u32x4*)((const char*)Wt + (woff + (unsigned)(32 * i * K + (kt) * 64) * 2u)); } } while (0)
; #define BSTORE(A_, B_, buf) do { _Pragma("unroll") for (int i = 0; i < 4; ++i) { \
;     *(u32x4*)&As[(buf) * GBUF + (srow + 32 * i) * LDT + sc8] = A_[i]; \
;     *(u32x4*)&Bs[(buf) * GBUF + (srow + 32 * i) * LDT + sc8] = B_[i]; } } while (0)
; template <int NK>
; DI void gemm_run(PF& pf, const u16* __restrict__ Ap, int lda, const u16* __restrict__ Wt, f32x16 (&acc)[2][2], char* smem) {
;     ...
; #pragma unroll
;   for (int kt = 0; kt < nk; kt += 2) {
;     BCOMP(0);
;     BSTORE(pf.a1, pf.b1, 1);
;     if (kt + 3 < nk) BLOAD(pf.a1, pf.b1, kt + 3);
;     __syncthreads();
;     BCOMP(1);
;     if (kt + 2 < nk) { BSTORE(pf.a0, pf.b0, 0); if (kt + 4 < nk) BLOAD(pf.a0, pf.b0, kt + 4); }
;     __syncthreads();
;   }
	ds_read_b128 v[224:227], v126 offset:0
	ds_read_b128 v[240:243], v128 offset:0
	ds_read_b128 v[244:247], v128 offset:1024
	ds_read_b128 v[248:251], v128 offset:2048
	ds_read_b128 v[156:159], v128 offset:3072
	ds_read_b128 v[228:231], v126 offset:1024
	ds_read_b128 v[232:235], v126 offset:2048
	ds_read_b128 v[236:239], v126 offset:3072
	ds_read_b128 v[160:163], v128 offset:8192
	ds_read_b128 v[164:167], v128 offset:9216
	ds_read_b128 v[168:171], v128 offset:10240
	ds_read_b128 v[122:125], v128 offset:11264
	s_waitcnt lgkmcnt(10)
	v_mfma_f32_16x16x32_bf16 v[2:5], v[224:227], v[240:243], v[2:5]
	s_waitcnt lgkmcnt(9)
	v_mfma_f32_16x16x32_bf16 v[6:9], v[224:227], v[244:247], v[6:9]
	s_waitcnt lgkmcnt(8)
	v_mfma_f32_16x16x32_bf16 v[10:13], v[224:227], v[248:251], v[10:13]
	s_waitcnt lgkmcnt(7)
	v_mfma_f32_16x16x32_bf16 v[14:17], v[224:227], v[156:159], v[14:17]
	s_waitcnt lgkmcnt(6)
	v_mfma_f32_16x16x32_bf16 v[18:21], v[228:231], v[240:243], v[18:21]
	v_mfma_f32_16x16x32_bf16 v[22:25], v[228:231], v[244:247], v[22:25]
	v_mfma_f32_16x16x32_bf16 v[26:29], v[228:231], v[248:251], v[26:29]
	v_mfma_f32_16x16x32_bf16 v[30:33], v[228:231], v[156:159], v[30:33]
	s_waitcnt lgkmcnt(5)
	v_mfma_f32_16x16x32_bf16 v[34:37], v[232:235], v[240:243], v[34:37]
	v_mfma_f32_16x16x32_bf16 v[38:41], v[232:235], v[244:247], v[38:41]
	v_mfma_f32_16x16x32_bf16 v[42:45], v[232:235], v[248:251], v[42:45]
	v_mfma_f32_16x16x32_bf16 v[46:49], v[232:235], v[156:159], v[46:49]
	s_waitcnt lgkmcnt(4)
	v_mfma_f32_16x16x32_bf16 v[50:53], v[236:239], v[240:243], v[50:53]
	v_mfma_f32_16x16x32_bf16 v[54:57], v[236:239], v[244:247], v[54:57]
	v_mfma_f32_16x16x32_bf16 v[58:61], v[236:239], v[248:251], v[58:61]
	v_mfma_f32_16x16x32_bf16 v[62:65], v[236:239], v[156:159], v[62:65]
	s_waitcnt lgkmcnt(3)
	v_mfma_f32_16x16x32_bf16 v[74:77], v[224:227], v[160:163], v[74:77]
	s_waitcnt lgkmcnt(2)
	v_mfma_f32_16x16x32_bf16 v[78:81], v[224:227], v[164:167], v[78:81]
	s_waitcnt lgkmcnt(1)
	v_mfma_f32_16x16x32_bf16 v[82:85], v[224:227], v[168:171], v[82:85]
	s_waitcnt lgkmcnt(0)
	v_mfma_f32_16x16x32_bf16 v[86:89], v[224:227], v[122:125], v[86:89]
	v_mfma_f32_16x16x32_bf16 v[90:93], v[228:231], v[160:163], v[90:93]
	v_mfma_f32_16x16x32_bf16 v[94:97], v[228:231], v[164:167], v[94:97]
	v_mfma_f32_16x16x32_bf16 v[98:101], v[228:231], v[168:171], v[98:101]
	v_mfma_f32_16x16x32_bf16 v[102:105], v[228:231], v[122:125], v[102:105]
	v_mfma_f32_16x16x32_bf16 v[106:109], v[232:235], v[160:163], v[106:109]
	v_mfma_f32_16x16x32_bf16 v[110:113], v[232:235], v[164:167], v[110:113]
	v_mfma_f32_16x16x32_bf16 v[114:117], v[232:235], v[168:171], v[114:117]
	v_mfma_f32_16x16x32_bf16 v[118:121], v[232:235], v[122:125], v[118:121]
	v_mfma_f32_16x16x32_bf16 v[208:211], v[236:239], v[160:163], v[208:211]
	v_mfma_f32_16x16x32_bf16 v[212:215], v[236:239], v[164:167], v[212:215]
	v_mfma_f32_16x16x32_bf16 v[216:219], v[236:239], v[168:171], v[216:219]
	v_mfma_f32_16x16x32_bf16 v[220:223], v[236:239], v[122:125], v[220:223]
	s_waitcnt vmcnt(0)
	s_barrier
	ds_read_b128 v[224:227], v126 offset:24576
	ds_read_b128 v[240:243], v128 offset:24576
	ds_read_b128 v[244:247], v128 offset:25600
	ds_read_b128 v[248:251], v128 offset:26624
	ds_read_b128 v[156:159], v128 offset:27648
	ds_read_b128 v[228:231], v126 offset:25600
	ds_read_b128 v[232:235], v126 offset:26624
	ds_read_b128 v[236:239], v126 offset:27648
	ds_read_b128 v[160:163], v128 offset:32768
	ds_read_b128 v[164:167], v128 offset:33792
	ds_read_b128 v[168:171], v128 offset:34816
	ds_read_b128 v[122:125], v128 offset:35840
	s_waitcnt lgkmcnt(10)
	v_mfma_f32_16x16x32_bf16 v[2:5], v[224:227], v[240:243], v[2:5]
	s_waitcnt lgkmcnt(9)
	v_mfma_f32_16x16x32_bf16 v[6:9], v[224:227], v[244:247], v[6:9]
	s_waitcnt lgkmcnt(8)
	v_mfma_f32_16x16x32_bf16 v[10:13], v[224:227], v[248:251], v[10:13]
	s_waitcnt lgkmcnt(7)
	v_mfma_f32_16x16x32_bf16 v[14:17], v[224:227], v[156:159], v[14:17]
	s_waitcnt lgkmcnt(6)
	v_mfma_f32_16x16x32_bf16 v[18:21], v[228:231], v[240:243], v[18:21]
	v_mfma_f32_16x16x32_bf16 v[22:25], v[228:231], v[244:247], v[22:25]
	v_mfma_f32_16x16x32_bf16 v[26:29], v[228:231], v[248:251], v[26:29]
	v_mfma_f32_16x16x32_bf16 v[30:33], v[228:231], v[156:159], v[30:33]
	s_waitcnt lgkmcnt(5)
	v_mfma_f32_16x16x32_bf16 v[34:37], v[232:235], v[240:243], v[34:37]
	v_mfma_f32_16x16x32_bf16 v[38:41], v[232:235], v[244:247], v[38:41]
	v_mfma_f32_16x16x32_bf16 v[42:45], v[232:235], v[248:251], v[42:45]
	v_mfma_f32_16x16x32_bf16 v[46:49], v[232:235], v[156:159], v[46:49]
	s_waitcnt lgkmcnt(4)
	v_mfma_f32_16x16x32_bf16 v[50:53], v[236:239], v[240:243], v[50:53]
	v_mfma_f32_16x16x32_bf16 v[54:57], v[236:239], v[244:247], v[54:57]
	v_mfma_f32_16x16x32_bf16 v[58:61], v[236:239], v[248:251], v[58:61]
	v_mfma_f32_16x16x32_bf16 v[62:65], v[236:239], v[156:159], v[62:65]
	s_waitcnt lgkmcnt(3)
	v_mfma_f32_16x16x32_bf16 v[74:77], v[224:227], v[160:163], v[74:77]
	s_waitcnt lgkmcnt(2)
	v_mfma_f32_16x16x32_bf16 v[78:81], v[224:227], v[164:167], v[78:81]
	s_waitcnt lgkmcnt(1)
	v_mfma_f32_16x16x32_bf16 v[82:85], v[224:227], v[168:171], v[82:85]
	s_waitcnt lgkmcnt(0)
	v_mfma_f32_16x16x32_bf16 v[86:89], v[224:227], v[122:125], v[86:89]
	v_mfma_f32_16x16x32_bf16 v[90:93], v[228:231], v[160:163], v[90:93]
	v_mfma_f32_16x16x32_bf16 v[94:97], v[228:231], v[164:167], v[94:97]
	v_mfma_f32_16x16x32_bf16 v[98:101], v[228:231], v[168:171], v[98:101]
	v_mfma_f32_16x16x32_bf16 v[102:105], v[228:231], v[122:125], v[102:105]
	v_mfma_f32_16x16x32_bf16 v[106:109], v[232:235], v[160:163], v[106:109]
	v_mfma_f32_16x16x32_bf16 v[110:113], v[232:235], v[164:167], v[110:113]
	v_mfma_f32_16x16x32_bf16 v[114:117], v[232:235], v[168:171], v[114:117]
	v_mfma_f32_16x16x32_bf16 v[118:121], v[232:235], v[122:125], v[118:121]
	v_mfma_f32_16x16x32_bf16 v[208:211], v[236:239], v[160:163], v[208:211]
	v_mfma_f32_16x16x32_bf16 v[212:215], v[236:239], v[164:167], v[212:215]
	v_mfma_f32_16x16x32_bf16 v[216:219], v[236:239], v[168:171], v[216:219]
	v_mfma_f32_16x16x32_bf16 v[220:223], v[236:239], v[122:125], v[220:223]
	s_barrier
	s_branch .Linp_post

; #define BLOAD(A_, B_, kt) do { _Pragma("unroll") for (int i = 0; i < 4; ++i) { \
;     A_[i] = *(const u32x4*)((const char*)Ap + (aoff + (unsigned)(32 * i * lda + (kt) * 64) * 2u)); B_[i] = *(const u32x4*)((const char*)Wt + (woff + (unsigned)(32 * i * K + (kt) * 64) * 2u)); } } while (0)
; #define BLOAD(A_, B_, kt) do { _Pragma("unroll") for (int i = 0; i < 4; ++i) { \
;     A_[i] = *(const u32x4*)((const char*)Ap + (aoff + (unsigned)(32 * i * lda + (kt) * 64) * 2u)); B_[i] = *(const u32x4*)((const char*)Wt + (woff + (unsigned)(32 * i * K + (kt) * 64) * 2u)); } } while (0)
; #define BSTORE(A_, B_, buf) do { _Pragma("unroll") for (int i = 0; i < 4; ++i) { \
;     *(u32x4*)&As[(buf) * GBUF + (srow + 32 * i) * LDT + sc8] = A_[i]; \
;     *(u32x4*)&Bs[(buf) * GBUF + (srow + 32 * i) * LDT + sc8] = B_[i]; } } while (0)
; template <int NK>
; DI void gemm_run(PF& pf, const u16* __restrict__ Ap, int lda, const u16* __restrict__ Wt, f32x16 (&acc)[2][2], char* smem) {
;     ...
; #pragma unroll
;   for (int kt = 0; kt < nk; kt += 2) {
;     BCOMP(0);
;     BSTORE(pf.a1, pf.b1, 1);
;     if (kt + 3 < nk) BLOAD(pf.a1, pf.b1, kt + 3);
;     __syncthreads();
;     BCOMP(1);
;     if (kt + 2 < nk) { BSTORE(pf.a0, pf.b0, 0); if (kt + 4 < nk) BLOAD(pf.a0, pf.b0, kt + 4); }
;     __syncthreads();
;   }
.Linpd_kloop:
	s_waitcnt vmcnt(6)
	s_barrier
	ds_read_b128 v[224:227], v126 offset:0
	ds_read_b128 v[240:243], v128 offset:0
	ds_read_b128 v[244:247], v128 offset:1024
	ds_read_b128 v[248:251], v128 offset:2048
	ds_read_b128 v[156:159], v128 offset:3072
	ds_read_b128 v[228:231], v126 offset:1024
	ds_read_b128 v[232:235], v126 offset:2048
	ds_read_b128 v[236:239], v126 offset:3072
	ds_read_b128 v[160:163], v128 offset:8192
	ds_read_b128 v[164:167], v128 offset:9216
	ds_read_b128 v[168:171], v128 offset:10240
	ds_read_b128 v[122:125], v128 offset:11264
	s_waitcnt lgkmcnt(10)
	v_mfma_f32_16x16x32_bf16 v[2:5], v[240:243], v[224:227], v[2:5]
	s_waitcnt lgkmcnt(9)
	v_mfma_f32_16x16x32_bf16 v[6:9], v[244:247], v[224:227], v[6:9]
	s_waitcnt lgkmcnt(8)
	v_mfma_f32_16x16x32_bf16 v[10:13], v[248:251], v[224:227], v[10:13]
	s_waitcnt lgkmcnt(7)
	v_mfma_f32_16x16x32_bf16 v[14:17], v[156:159], v[224:227], v[14:17]
	s_waitcnt lgkmcnt(6)
	v_mfma_f32_16x16x32_bf16 v[18:21], v[240:243], v[228:231], v[18:21]
	v_mfma_f32_16x16x32_bf16 v[22:25], v[244:247], v[228:231], v[22:25]
	v_mfma_f32_16x16x32_bf16 v[26:29], v[248:251], v[228:231], v[26:29]
	v_mfma_f32_16x16x32_bf16 v[30:33], v[156:159], v[228:231], v[30:33]
	s_waitcnt lgkmcnt(5)
	v_mfma_f32_16x16x32_bf16 v[34:37], v[240:243], v[232:235], v[34:37]
	v_mfma_f32_16x16x32_bf16 v[38:41], v[244:247], v[232:235], v[38:41]
	v_mfma_f32_16x16x32_bf16 v[42:45], v[248:251], v[232:235], v[42:45]
	v_mfma_f32_16x16x32_bf16 v[46:49], v[156:159], v[232:235], v[46:49]
	s_waitcnt lgkmcnt(4)
	v_mfma_f32_16x16x32_bf16 v[50:53], v[240:243], v[236:239], v[50:53]
	v_mfma_f32_16x16x32_bf16 v[54:57], v[244:247], v[236:239], v[54:57]
	v_mfma_f32_16x16x32_bf16 v[58:61], v[248:251], v[236:239], v[58:61]
	v_mfma_f32_16x16x32_bf16 v[62:65], v[156:159], v[236:239], v[62:65]
	s_add_u32 m0, s46, 0xc000
	s_add_u32 s48, s48, 0x100000
	s_addc_u32 s49, s49, 0
	global_load_lds_dwordx4 v138, s[48:49]
	global_load_lds_dwordx4 v139, s[48:49] offset:1024
	s_add_u32 m0, s47, 0xc000
	s_add_u32 s50, s50, s13
	s_addc_u32 s51, s51, 0
	global_load_lds_dwordx4 v140, s[50:51]
	global_load_lds_dwordx4 v141, s[50:51] offset:1024
	global_load_lds_dwordx4 v142, s[50:51] offset:2048
	global_load_lds_dwordx4 v143, s[50:51] offset:3072
	s_waitcnt lgkmcnt(3)
	v_mfma_f32_16x16x32_bf16 v[74:77], v[160:163], v[224:227], v[74:77]
	s_waitcnt lgkmcnt(2)
	v_mfma_f32_16x16x32_bf16 v[78:81], v[164:167], v[224:227], v[78:81]
	s_waitcnt lgkmcnt(1)
	v_mfma_f32_16x16x32_bf16 v[82:85], v[168:171], v[224:227], v[82:85]
	s_waitcnt lgkmcnt(0)
	v_mfma_f32_16x16x32_bf16 v[86:89], v[122:125], v[224:227], v[86:89]
	v_mfma_f32_16x16x32_bf16 v[90:93], v[160:163], v[228:231], v[90:93]
	v_mfma_f32_16x16x32_bf16 v[94:97], v[164:167], v[228:231], v[94:97]
	v_mfma_f32_16x16x32_bf16 v[98:101], v[168:171], v[228:231], v[98:101]
	v_mfma_f32_16x16x32_bf16 v[102:105], v[122:125], v[228:231], v[102:105]
	v_mfma_f32_16x16x32_bf16 v[106:109], v[160:163], v[232:235], v[106:109]
	v_mfma_f32_16x16x32_bf16 v[110:113], v[164:167], v[232:235], v[110:113]
	v_mfma_f32_16x16x32_bf16 v[114:117], v[168:171], v[232:235], v[114:117]
	v_mfma_f32_16x16x32_bf16 v[118:121], v[122:125], v[232:235], v[118:121]
	v_mfma_f32_16x16x32_bf16 v[208:211], v[160:163], v[236:239], v[208:211]
	v_mfma_f32_16x16x32_bf16 v[212:215], v[164:167], v[236:239], v[212:215]
	v_mfma_f32_16x16x32_bf16 v[216:219], v[168:171], v[236:239], v[216:219]
	v_mfma_f32_16x16x32_bf16 v[220:223], v[122:125], v[236:239], v[220:223]
	s_waitcnt vmcnt(6)
	s_barrier
	ds_read_b128 v[224:227], v126 offset:24576
	ds_read_b128 v[240:243], v128 offset:24576
	ds_read_b128 v[244:247], v128 offset:25600
	ds_read_b128 v[248:251], v128 offset:26624
	ds_read_b128 v[156:159], v128 offset:27648
	ds_read_b128 v[228:231], v126 offset:25600
	ds_read_b128 v[232:235], v126 offset:26624
	ds_read_b128 v[236:239], v126 offset:27648
	ds_read_b128 v[160:163], v128 offset:32768
	ds_read_b128 v[164:167], v128 offset:33792
	ds_read_b128 v[168:171], v128 offset:34816
	ds_read_b128 v[122:125], v128 offset:35840
	s_waitcnt lgkmcnt(10)
	v_mfma_f32_16x16x32_bf16 v[2:5], v[240:243], v[224:227], v[2:5]
	s_waitcnt lgkmcnt(9)
	v_mfma_f32_16x16x32_bf16 v[6:9], v[244:247], v[224:227], v[6:9]
	s_waitcnt lgkmcnt(8)
	v_mfma_f32_16x16x32_bf16 v[10:13], v[248:251], v[224:227], v[10:13]
	s_waitcnt lgkmcnt(7)
	v_mfma_f32_16x16x32_bf16 v[14:17], v[156:159], v[224:227], v[14:17]
	s_waitcnt lgkmcnt(6)
	v_mfma_f32_16x16x32_bf16 v[18:21], v[240:243], v[228:231], v[18:21]
	v_mfma_f32_16x16x32_bf16 v[22:25], v[244:247], v[228:231], v[22:25]
	v_mfma_f32_16x16x32_bf16 v[26:29], v[248:251], v[228:231], v[26:29]
	v_mfma_f32_16x16x32_bf16 v[30:33], v[156:159], v[228:231], v[30:33]
	s_waitcnt lgkmcnt(5)
	v_mfma_f32_16x16x32_bf16 v[34:37], v[240:243], v[232:235], v[34:37]
	v_mfma_f32_16x16x32_bf16 v[38:41], v[244:247], v[232:235], v[38:41]
	v_mfma_f32_16x16x32_bf16 v[42:45], v[248:251], v[232:235], v[42:45]
	v_mfma_f32_16x16x32_bf16 v[46:49], v[156:159], v[232:235], v[46:49]
	s_waitcnt lgkmcnt(4)
	v_mfma_f32_16x16x32_bf16 v[50:53], v[240:243], v[236:239], v[50:53]
	v_mfma_f32_16x16x32_bf16 v[54:57], v[244:247], v[236:239], v[54:57]
	v_mfma_f32_16x16x32_bf16 v[58:61], v[248:251], v[236:239], v[58:61]
	v_mfma_f32_16x16x32_bf16 v[62:65], v[156:159], v[236:239], v[62:65]
	s_add_u32 m0, s46, 0x0
	s_add_u32 s48, s48, 0x100000
	s_addc_u32 s49, s49, 0
	global_load_lds_dwordx4 v138, s[48:49]
	global_load_lds_dwordx4 v139, s[48:49] offset:1024
	s_add_u32 m0, s47, 0x0
	s_add_u32 s50, s50, s13
	s_addc_u32 s51, s51, 0
	global_load_lds_dwordx4 v140, s[50:51]
	global_load_lds_dwordx4 v141, s[50:51] offset:1024
	global_load_lds_dwordx4 v142, s[50:51] offset:2048
	global_load_lds_dwordx4 v143, s[50:51] offset:3072
	s_waitcnt lgkmcnt(3)
	v_mfma_f32_16x16x32_bf16 v[74:77], v[160:163], v[224:227], v[74:77]
	s_waitcnt lgkmcnt(2)
	v_mfma_f32_16x16x32_bf16 v[78:81], v[164:167], v[224:227], v[78:81]
	s_waitcnt lgkmcnt(1)
	v_mfma_f32_16x16x32_bf16 v[82:85], v[168:171], v[224:227], v[82:85]
	s_waitcnt lgkmcnt(0)
	v_mfma_f32_16x16x32_bf16 v[86:89], v[122:125], v[224:227], v[86:89]
	v_mfma_f32_16x16x32_bf16 v[90:93], v[160:163], v[228:231], v[90:93]
	v_mfma_f32_16x16x32_bf16 v[94:97], v[164:167], v[228:231], v[94:97]
	v_mfma_f32_16x16x32_bf16 v[98:101], v[168:171], v[228:231], v[98:101]
	v_mfma_f32_16x16x32_bf16 v[102:105], v[122:125], v[228:231], v[102:105]
	v_mfma_f32_16x16x32_bf16 v[106:109], v[160:163], v[232:235], v[106:109]
	v_mfma_f32_16x16x32_bf16 v[110:113], v[164:167], v[232:235], v[110:113]
	v_mfma_f32_16x16x32_bf16 v[114:117], v[168:171], v[232:235], v[114:117]
	v_mfma_f32_16x16x32_bf16 v[118:121], v[122:125], v[232:235], v[118:121]
	v_mfma_f32_16x16x32_bf16 v[208:211], v[160:163], v[236:239], v[208:211]
	v_mfma_f32_16x16x32_bf16 v[212:215], v[164:167], v[236:239], v[212:215]
	v_mfma_f32_16x16x32_bf16 v[216:219], v[168:171], v[236:239], v[216:219]
	v_mfma_f32_16x16x32_bf16 v[220:223], v[122:125], v[236:239], v[220:223]
	s_waitcnt vmcnt(6)
	s_barrier
; #define BLOAD(A_, B_, kt) do { _Pragma("unroll") for (int i = 0; i < 4; ++i) { \
;     A_[i] = *(const u32x4*)((const char*)Ap + (aoff + (unsigned)(32 * i * lda + (kt) * 64) * 2u)); B_[i] = *(const u32x4*)((const char*)Wt + (woff + (unsigned)(32 * i * K + (kt) * 64) * 2u)); } } while (0)
; #define BLOAD(A_, B_, kt) do { _Pragma("unroll") for (int i = 0; i < 4; ++i) { \
;     A_[i] = *(const u32x4*)((const char*)Ap + (aoff + (unsigned)(32 * i * lda + (kt) * 64) * 2u)); B_[i] = *(const u32x4*)((const char*)Wt + (woff + (unsigned)(32 * i * K + (kt) * 64) * 2u)); } } while (0)
; #define BSTORE(A_, B_, buf) do { _Pragma("unroll") for (int i = 0; i < 4; ++i) { \
;     *(u32x4*)&As[(buf) * GBUF + (srow + 32 * i) * LDT + sc8] = A_[i]; \
;     *(u32x4*)&Bs[(buf) * GBUF + (srow + 32 * i) * LDT + sc8] = B_[i]; } } while (0)
; template <int NK>
; DI void gemm_run(PF& pf, const u16* __restrict__ Ap, int lda, const u16* __restrict__ Wt, f32x16 (&acc)[2][2], char* smem) {
;     ...
; #pragma unroll
;   for (int kt = 0; kt < nk; kt += 2) {
;     BCOMP(0);
;     BSTORE(pf.a1, pf.b1, 1);
;     if (kt + 3 < nk) BLOAD(pf.a1, pf.b1, kt + 3);
;     __syncthreads();
;     BCOMP(1);
;     if (kt + 2 < nk) { BSTORE(pf.a0, pf.b0, 0); if (kt + 4 < nk) BLOAD(pf.a0, pf.b0, kt + 4); }
;     __syncthreads();
;   }
	ds_read_b128 v[224:227], v126 offset:49152
	ds_read_b128 v[240:243], v128 offset:49152
	ds_read_b128 v[244:247], v128 offset:50176
	ds_read_b128 v[248:251], v128 offset:51200
	ds_read_b128 v[156:159], v128 offset:52224
	ds_read_b128 v[228:231], v126 offset:50176
	ds_read_b128 v[232:235], v126 offset:51200
	ds_read_b128 v[236:239], v126 offset:52224
	ds_read_b128 v[160:163], v128 offset:57344
	ds_read_b128 v[164:167], v128 offset:58368
	ds_read_b128 v[168:171], v128 offset:59392
	ds_read_b128 v[122:125], v128 offset:60416
	s_waitcnt lgkmcnt(10)
	v_mfma_f32_16x16x32_bf16 v[2:5], v[240:243], v[224:227], v[2:5]
	s_waitcnt lgkmcnt(9)
	v_mfma_f32_16x16x32_bf16 v[6:9], v[244:247], v[224:227], v[6:9]
	s_waitcnt lgkmcnt(8)
	v_mfma_f32_16x16x32_bf16 v[10:13], v[248:251], v[224:227], v[10:13]
	s_waitcnt lgkmcnt(7)
	v_mfma_f32_16x16x32_bf16 v[14:17], v[156:159], v[224:227], v[14:17]
	s_waitcnt lgkmcnt(6)
	v_mfma_f32_16x16x32_bf16 v[18:21], v[240:243], v[228:231], v[18:21]
	v_mfma_f32_16x16x32_bf16 v[22:25], v[244:247], v[228:231], v[22:25]
	v_mfma_f32_16x16x32_bf16 v[26:29], v[248:251], v[228:231], v[26:29]
	v_mfma_f32_16x16x32_bf16 v[30:33], v[156:159], v[228:231], v[30:33]
	s_waitcnt lgkmcnt(5)
	v_mfma_f32_16x16x32_bf16 v[34:37], v[240:243], v[232:235], v[34:37]
	v_mfma_f32_16x16x32_bf16 v[38:41], v[244:247], v[232:235], v[38:41]
	v_mfma_f32_16x16x32_bf16 v[42:45], v[248:251], v[232:235], v[42:45]
	v_mfma_f32_16x16x32_bf16 v[46:49], v[156:159], v[232:235], v[46:49]
	s_waitcnt lgkmcnt(4)
	v_mfma_f32_16x16x32_bf16 v[50:53], v[240:243], v[236:239], v[50:53]
	v_mfma_f32_16x16x32_bf16 v[54:57], v[244:247], v[236:239], v[54:57]
	v_mfma_f32_16x16x32_bf16 v[58:61], v[248:251], v[236:239], v[58:61]
	v_mfma_f32_16x16x32_bf16 v[62:65], v[156:159], v[236:239], v[62:65]
	s_add_u32 m0, s46, 0x6000
	s_add_u32 s48, s48, 0x100000
	s_addc_u32 s49, s49, 0
	global_load_lds_dwordx4 v138, s[48:49]
	global_load_lds_dwordx4 v139, s[48:49] offset:1024
	s_add_u32 m0, s47, 0x6000
	s_add_u32 s50, s50, s13
	s_addc_u32 s51, s51, 0
	global_load_lds_dwordx4 v140, s[50:51]
	global_load_lds_dwordx4 v141, s[50:51] offset:1024
	global_load_lds_dwordx4 v142, s[50:51] offset:2048
	global_load_lds_dwordx4 v143, s[50:51] offset:3072
	s_waitcnt lgkmcnt(3)
	v_mfma_f32_16x16x32_bf16 v[74:77], v[160:163], v[224:227], v[74:77]
	s_waitcnt lgkmcnt(2)
	v_mfma_f32_16x16x32_bf16 v[78:81], v[164:167], v[224:227], v[78:81]
	s_waitcnt lgkmcnt(1)
	v_mfma_f32_16x16x32_bf16 v[82:85], v[168:171], v[224:227], v[82:85]
	s_waitcnt lgkmcnt(0)
	v_mfma_f32_16x16x32_bf16 v[86:89], v[122:125], v[224:227], v[86:89]
	v_mfma_f32_16x16x32_bf16 v[90:93], v[160:163], v[228:231], v[90:93]
	v_mfma_f32_16x16x32_bf16 v[94:97], v[164:167], v[228:231], v[94:97]
	v_mfma_f32_16x16x32_bf16 v[98:101], v[168:171], v[228:231], v[98:101]
	v_mfma_f32_16x16x32_bf16 v[102:105], v[122:125], v[228:231], v[102:105]
	v_mfma_f32_16x16x32_bf16 v[106:109], v[160:163], v[232:235], v[106:109]
	v_mfma_f32_16x16x32_bf16 v[110:113], v[164:167], v[232:235], v[110:113]
	v_mfma_f32_16x16x32_bf16 v[114:117], v[168:171], v[232:235], v[114:117]
	v_mfma_f32_16x16x32_bf16 v[118:121], v[122:125], v[232:235], v[118:121]
	v_mfma_f32_16x16x32_bf16 v[208:211], v[160:163], v[236:239], v[208:211]
	v_mfma_f32_16x16x32_bf16 v[212:215], v[164:167], v[236:239], v[212:215]
	v_mfma_f32_16x16x32_bf16 v[216:219], v[168:171], v[236:239], v[216:219]
	v_mfma_f32_16x16x32_bf16 v[220:223], v[122:125], v[236:239], v[220:223]
	s_sub_u32 s12, s12, 1
	s_cmp_lg_u32 s12, 0
	s_cbranch_scc1 .Linpd_kloop
	s_waitcnt vmcnt(6)
	s_barrier
; #define BLOAD(A_, B_, kt) do { _Pragma("unroll") for (int i = 0; i < 4; ++i) { \
;     A_[i] = *(const u32x4*)((const char*)Ap + (aoff + (unsigned)(32 * i * lda + (kt) * 64) * 2u)); B_[i] = *(const u32x4*)((const char*)Wt + (woff + (unsigned)(32 * i * K + (kt) * 64) * 2u)); } } while (0)
; #define BLOAD(A_, B_, kt) do { _Pragma("unroll") for (int i = 0; i < 4; ++i) { \
;     A_[i] = *(const u32x4*)((const char*)Ap + (aoff + (unsigned)(32 * i * lda + (kt) * 64) * 2u)); B_[i] = *(const u32x4*)((const char*)Wt + (woff + (unsigned)(32 * i * K + (kt) * 64) * 2u)); } } while (0)
; #define BSTORE(A_, B_, buf) do { _Pragma("unroll") for (int i = 0; i < 4; ++i) { \
;     *(u32x4*)&As[(buf) * GBUF + (srow + 32 * i) * LDT + sc8] = A_[i]; \
;     *(u32x4*)&Bs[(buf) * GBUF + (srow + 32 * i) * LDT + sc8] = B_[i]; } } while (0)
; template <int NK>
; DI void gemm_run(PF& pf, const u16* __restrict__ Ap, int lda, const u16* __restrict__ Wt, f32x16 (&acc)[2][2], char* smem) {
;     ...
; #pragma unroll
;   for (int kt = 0; kt < nk; kt += 2) {
;     BCOMP(0);
;     BSTORE(pf.a1, pf.b1, 1);
;     if (kt + 3 < nk) BLOAD(pf.a1, pf.b1, kt + 3);
;     __syncthreads();
;     BCOMP(1);
;     if (kt + 2 < nk) { BSTORE(pf.a0, pf.b0, 0); if (kt + 4 < nk) BLOAD(pf.a0, pf.b0, kt + 4); }
;     __syncthreads();
;   }
	ds_read_b128 v[224:227], v126 offset:0
	ds_read_b128 v[240:243], v128 offset:0
	ds_read_b128 v[244:247], v128 offset:1024
	ds_read_b128 v[248:251], v128 offset:2048
	ds_read_b128 v[156:159], v128 offset:3072
	ds_read_b128 v[228:231], v126 offset:1024
	ds_read_b128 v[232:235], v126 offset:2048
	ds_read_b128 v[236:239], v126 offset:3072
	ds_read_b128 v[160:163], v128 offset:8192
	ds_read_b128 v[164:167], v128 offset:9216
	ds_read_b128 v[168:171], v128 offset:10240
	ds_read_b128 v[122:125], v128 offset:11264
	s_waitcnt lgkmcnt(10)
	v_mfma_f32_16x16x32_bf16 v[2:5], v[240:243], v[224:227], v[2:5]
	s_waitcnt lgkmcnt(9)
	v_mfma_f32_16x16x32_bf16 v[6:9], v[244:247], v[224:227], v[6:9]
	s_waitcnt lgkmcnt(8)
	v_mfma_f32_16x16x32_bf16 v[10:13], v[248:251], v[224:227], v[10:13]
	s_waitcnt lgkmcnt(7)
	v_mfma_f32_16x16x32_bf16 v[14:17], v[156:159], v[224:227], v[14:17]
	s_waitcnt lgkmcnt(6)
	v_mfma_f32_16x16x32_bf16 v[18:21], v[240:243], v[228:231], v[18:21]
	v_mfma_f32_16x16x32_bf16 v[22:25], v[244:247], v[228:231], v[22:25]
	v_mfma_f32_16x16x32_bf16 v[26:29], v[248:251], v[228:231], v[26:29]
	v_mfma_f32_16x16x32_bf16 v[30:33], v[156:159], v[228:231], v[30:33]
	s_waitcnt lgkmcnt(5)
	v_mfma_f32_16x16x32_bf16 v[34:37], v[240:243], v[232:235], v[34:37]
	v_mfma_f32_16x16x32_bf16 v[38:41], v[244:247], v[232:235], v[38:41]
	v_mfma_f32_16x16x32_bf16 v[42:45], v[248:251], v[232:235], v[42:45]
	v_mfma_f32_16x16x32_bf16 v[46:49], v[156:159], v[232:235], v[46:49]
	s_waitcnt lgkmcnt(4)
	v_mfma_f32_16x16x32_bf16 v[50:53], v[240:243], v[236:239], v[50:53]
	v_mfma_f32_16x16x32_bf16 v[54:57], v[244:247], v[236:239], v[54:57]
	v_mfma_f32_16x16x32_bf16 v[58:61], v[248:251], v[236:239], v[58:61]
	v_mfma_f32_16x16x32_bf16 v[62:65], v[156:159], v[236:239], v[62:65]
	s_waitcnt lgkmcnt(3)
	v_mfma_f32_16x16x32_bf16 v[74:77], v[160:163], v[224:227], v[74:77]
	s_waitcnt lgkmcnt(2)
	v_mfma_f32_16x16x32_bf16 v[78:81], v[164:167], v[224:227], v[78:81]
	s_waitcnt lgkmcnt(1)
	v_mfma_f32_16x16x32_bf16 v[82:85], v[168:171], v[224:227], v[82:85]
	s_waitcnt lgkmcnt(0)
	v_mfma_f32_16x16x32_bf16 v[86:89], v[122:125], v[224:227], v[86:89]
	v_mfma_f32_16x16x32_bf16 v[90:93], v[160:163], v[228:231], v[90:93]
	v_mfma_f32_16x16x32_bf16 v[94:97], v[164:167], v[228:231], v[94:97]
	v_mfma_f32_16x16x32_bf16 v[98:101], v[168:171], v[228:231], v[98:101]
	v_mfma_f32_16x16x32_bf16 v[102:105], v[122:125], v[228:231], v[102:105]
	v_mfma_f32_16x16x32_bf16 v[106:109], v[160:163], v[232:235], v[106:109]
	v_mfma_f32_16x16x32_bf16 v[110:113], v[164:167], v[232:235], v[110:113]
	v_mfma_f32_16x16x32_bf16 v[114:117], v[168:171], v[232:235], v[114:117]
	v_mfma_f32_16x16x32_bf16 v[118:121], v[122:125], v[232:235], v[118:121]
	v_mfma_f32_16x16x32_bf16 v[208:211], v[160:163], v[236:239], v[208:211]
	v_mfma_f32_16x16x32_bf16 v[212:215], v[164:167], v[236:239], v[212:215]
	v_mfma_f32_16x16x32_bf16 v[216:219], v[168:171], v[236:239], v[216:219]
	v_mfma_f32_16x16x32_bf16 v[220:223], v[122:125], v[236:239], v[220:223]
	s_waitcnt vmcnt(0)
	s_barrier
	ds_read_b128 v[224:227], v126 offset:24576
	ds_read_b128 v[240:243], v128 offset:24576
	ds_read_b128 v[244:247], v128 offset:25600
	ds_read_b128 v[248:251], v128 offset:26624
	ds_read_b128 v[156:159], v128 offset:27648
	ds_read_b128 v[228:231], v126 offset:25600
	ds_read_b128 v[232:235], v126 offset:26624
	ds_read_b128 v[236:239], v126 offset:27648
	ds_read_b128 v[160:163], v128 offset:32768
	ds_read_b128 v[164:167], v128 offset:33792
	ds_read_b128 v[168:171], v128 offset:34816
	ds_read_b128 v[122:125], v128 offset:35840
	s_waitcnt lgkmcnt(10)
	v_mfma_f32_16x16x32_bf16 v[2:5], v[240:243], v[224:227], v[2:5]
	s_waitcnt lgkmcnt(9)
	v_mfma_f32_16x16x32_bf16 v[6:9], v[244:247], v[224:227], v[6:9]
	s_waitcnt lgkmcnt(8)
	v_mfma_f32_16x16x32_bf16 v[10:13], v[248:251], v[224:227], v[10:13]
	s_waitcnt lgkmcnt(7)
	v_mfma_f32_16x16x32_bf16 v[14:17], v[156:159], v[224:227], v[14:17]
	s_waitcnt lgkmcnt(6)
	v_mfma_f32_16x16x32_bf16 v[18:21], v[240:243], v[228:231], v[18:21]
	v_mfma_f32_16x16x32_bf16 v[22:25], v[244:247], v[228:231], v[22:25]
	v_mfma_f32_16x16x32_bf16 v[26:29], v[248:251], v[228:231], v[26:29]
	v_mfma_f32_16x16x32_bf16 v[30:33], v[156:159], v[228:231], v[30:33]
	s_waitcnt lgkmcnt(5)
	v_mfma_f32_16x16x32_bf16 v[34:37], v[240:243], v[232:235], v[34:37]
	v_mfma_f32_16x16x32_bf16 v[38:41], v[244:247], v[232:235], v[38:41]
	v_mfma_f32_16x16x32_bf16 v[42:45], v[248:251], v[232:235], v[42:45]
	v_mfma_f32_16x16x32_bf16 v[46:49], v[156:159], v[232:235], v[46:49]
	s_waitcnt lgkmcnt(4)
	v_mfma_f32_16x16x32_bf16 v[50:53], v[240:243], v[236:239], v[50:53]
	v_mfma_f32_16x16x32_bf16 v[54:57], v[244:247], v[236:239], v[54:57]
	v_mfma_f32_16x16x32_bf16 v[58:61], v[248:251], v[236:239], v[58:61]
	v_mfma_f32_16x16x32_bf16 v[62:65], v[156:159], v[236:239], v[62:65]
	s_waitcnt lgkmcnt(3)
	v_mfma_f32_16x16x32_bf16 v[74:77], v[160:163], v[224:227], v[74:77]
	s_waitcnt lgkmcnt(2)
	v_mfma_f32_16x16x32_bf16 v[78:81], v[164:167], v[224:227], v[78:81]
	s_waitcnt lgkmcnt(1)
	v_mfma_f32_16x16x32_bf16 v[82:85], v[168:171], v[224:227], v[82:85]
	s_waitcnt lgkmcnt(0)
	v_mfma_f32_16x16x32_bf16 v[86:89], v[122:125], v[224:227], v[86:89]
	v_mfma_f32_16x16x32_bf16 v[90:93], v[160:163], v[228:231], v[90:93]
	v_mfma_f32_16x16x32_bf16 v[94:97], v[164:167], v[228:231], v[94:97]
	v_mfma_f32_16x16x32_bf16 v[98:101], v[168:171], v[228:231], v[98:101]
	v_mfma_f32_16x16x32_bf16 v[102:105], v[122:125], v[228:231], v[102:105]
	v_mfma_f32_16x16x32_bf16 v[106:109], v[160:163], v[232:235], v[106:109]
	v_mfma_f32_16x16x32_bf16 v[110:113], v[164:167], v[232:235], v[110:113]
	v_mfma_f32_16x16x32_bf16 v[114:117], v[168:171], v[232:235], v[114:117]
	v_mfma_f32_16x16x32_bf16 v[118:121], v[122:125], v[232:235], v[118:121]
	v_mfma_f32_16x16x32_bf16 v[208:211], v[160:163], v[236:239], v[208:211]
	v_mfma_f32_16x16x32_bf16 v[212:215], v[164:167], v[236:239], v[212:215]
	v_mfma_f32_16x16x32_bf16 v[216:219], v[168:171], v[236:239], v[216:219]
	v_mfma_f32_16x16x32_bf16 v[220:223], v[122:125], v[236:239], v[220:223]
	s_barrier
	s_branch .Linp_post
